# v37 plus first-K-iteration DMA waits W1/W2 skipped (prefetch already confirmed by the epilogue's vmcnt(0)); prologue drains to vmcnt(0)
# baseline (speedup 1.0000x reference)
; #define PG8_STAGE(bufoff, gbase, voff) do { _Pragma("unroll") for (int _i = 0; _i < 2; ++_i) \
;         __builtin_amdgcn_global_load_lds((const unsigned*)((const char*)(gbase) + (voff)[_i]), (PG8_LAS unsigned*)(lds + (bufoff) + ldsw + _i * 8192), 16, 0, 0); } while (0)
; #define PG8_WAIT_V(n) asm volatile("s_waitcnt vmcnt(" #n ")" ::: "memory")
; #define PG8_BAR __builtin_amdgcn_s_barrier()
; template <class Epi, class Sched, bool ALIGN_EPI = false, bool SP2 = false, bool TILED = false>
; __device__ __forceinline__ void gemm_phase(PG8_LAS unsigned char* lds, const Gemm g, const Sched& S, const Epi& E) {
;     ...
;     for (int i = 0; i < 2; ++i) { int R, C; stage_rc(tid * 16 + i * 8192, R, C); const int Rb = Epi::PERM ? ((R & ~31) + perm32(R & 31)) : R;
;         const int rs = TILED ? BK : K; voffA[i] = (unsigned)(R * rs + C) * 2u; voffB[i] = (unsigned)(Rb * rs + C) * 2u; }
;     const size_t kstep = TILED ? (size_t)(BM * BK * 2) : (size_t)(BK * 2);
;     const size_t hstep = TILED ? (size_t)(HALF * BK * 2) : (size_t)HALF * K * 2;
;     const size_t tstep = TILED ? (size_t)(K / BK) * (BM * BK * 2) : 2 * hstep;
;     const unsigned ldsw = (unsigned)wid * 1024u;
;     const int aoff = lds_byte(wr * 64 + fr, fq * 8), boff = lds_byte(wc * 32 + fr, fq * 8);
;     ...
;     Unit cur, nxt; int ui = 0;
;     if (!S.next(0, cur)) return;
;     f32x4 acc[2][2][4][2];
; #pragma unroll
;     for (int a = 0; a < 2; ++a)
; #pragma unroll
;         for (int b = 0; b < 2; ++b)
; #pragma unroll
;             for (int m = 0; m < 4; ++m)
; #pragma unroll
;                 for (int n = 0; n < 2; ++n) acc[a][b][m][n] = (f32x4){0.f, 0.f, 0.f, 0.f};
;     bf16x8 At[4][2], B0[2][2], B1[2][2];
;     const char* cA = (const char*)g.A + (size_t)cur.pm * tstep; const char* cB = (const char*)g.Bt + (size_t)cur.pn * tstep;
;     S.a_ready(cur);
;     if constexpr (SP2) {
;         PG8_STAGE(PG8_SB(0, 0), cB, voffB); PG8_STAGE(PG8_SB(0, 1), cB + hstep, voffB); PG8_STAGE(PG8_SA(0, 0), cA, voffA); PG8_STAGE(PG8_SA(0, 1), cA + hstep, voffA);
;         if (wr == 1) PG8_BAR;
;         PG8_WAIT_V(2); PG8_BAR;
;         PG8_STAGE(PG8_SB(1, 0), cB + kstep, voffB); PG8_STAGE(PG8_SA(1, 0), cA + kstep, voffA); PG8_STAGE(PG8_SB(1, 1), cB + hstep + kstep, voffB);
;         PG8_WAIT_V(6); PG8_BAR;
.LBB0_94:
	v_readlane_b32 s18, v249, 3
	v_readlane_b32 s19, v249, 4
	v_mov_b32_e32 v145, v177
	v_mov_b32_e32 v149, v177
	v_lshl_add_u64 v[8:9], s[18:19], 0, v[176:177]
	v_lshl_add_u64 v[10:11], s[18:19], 0, v[144:145]
	s_add_i32 m0, s56, 0x18000
	v_lshl_add_u64 v[8:9], v[8:9], 0, s[26:27]
	s_waitcnt vmcnt(0)
	v_lshl_add_u64 v[12:13], s[0:1], 0, v[148:149]
	v_mov_b32_e32 v147, v177
	s_waitcnt vmcnt(2)
	s_barrier
	global_load_lds_dwordx4 v[8:9], off
	v_lshl_add_u64 v[8:9], v[10:11], 0, s[26:27]
	s_add_i32 m0, s56, 0x1a000
	s_add_i32 s66, s56, 0x8000
	v_lshl_add_u64 v[14:15], s[0:1], 0, v[146:147]
	global_load_lds_dwordx4 v[8:9], off
	v_lshl_add_u64 v[8:9], v[12:13], 0, s[26:27]
	s_mov_b32 m0, s66
	s_add_i32 s67, s56, 0xa000
	v_readlane_b32 s8, v249, 5
	global_load_lds_dwordx4 v[8:9], off
	v_lshl_add_u64 v[8:9], v[14:15], 0, s[26:27]
	s_mov_b32 m0, s67
	v_readlane_b32 s9, v249, 6
	global_load_lds_dwordx4 v[8:9], off
	s_add_i32 m0, s56, 0x1c000
	v_lshl_add_u64 v[8:9], s[8:9], 0, v[176:177]
	global_load_lds_dwordx4 v[8:9], off
	v_lshl_add_u64 v[8:9], s[8:9], 0, v[144:145]
	s_add_i32 m0, s56, 0x1e000
	v_and_b32_e32 v7, 15, v0
	global_load_lds_dwordx4 v[8:9], off
	v_lshrrev_b32_e32 v8, 1, v0
	v_and_b32_e32 v8, 24, v8
	v_lshlrev_b32_e32 v9, 1, v8
	v_lshlrev_b32_e32 v0, 2, v0
	s_lshl_b32 s5, s5, 5
	v_lshl_or_b32 v164, s6, 6, v7
	v_lshl_or_b32 v7, v7, 6, v9
	s_lshl_b32 s6, s6, 13
	v_and_b32_e32 v0, 32, v0
	s_and_b32 s5, s5, 0x60
	v_bitop3_b32 v9, v7, s6, v0 bitop3:0xde
	s_lshl_b32 s6, s5, 7
	v_bitop3_b32 v165, v7, s6, v0 bitop3:0xde
	v_lshlrev_b32_e32 v0, 14, v5
	v_and_b32_e32 v0, 0xffff8000, v0
	v_lshl_add_u32 v0, v4, 11, v0
	v_and_b32_e32 v4, 1, v5
	v_lshl_or_b32 v0, v4, 6, v0
	v_lshl_add_u32 v150, v6, 1, v0
	v_lshlrev_b32_e32 v0, 14, v1
	v_and_b32_e32 v0, 0xffff8000, v0
	s_waitcnt vmcnt(0)
	v_lshl_add_u32 v0, v2, 11, v0
	v_and_b32_e32 v1, 1, v1
	s_cmpk_lt_u32 s4, 0x100
	v_lshl_or_b32 v0, v1, 6, v0
	v_readlane_b32 s6, v250, 60
	s_cselect_b64 s[16:17], -1, 0
	v_or_b32_e32 v166, s5, v8
	v_mov_b32_e32 v151, v177
	v_lshl_add_u32 v152, v3, 1, v0
	v_mov_b32_e32 v153, v177
	s_mov_b32 s72, 0
	v_add_u32_e32 v167, 0, v9
	v_readlane_b32 s5, v250, 32
	s_mov_b32 s4, s6
	s_movk_i32 s35, 0x2a1
	s_barrier
	v_readlane_b32 s7, v250, 61
	s_branch .LBB0_97

; #define PG8_STAGE(bufoff, gbase, voff) do { _Pragma("unroll") for (int _i = 0; _i < 2; ++_i) \
;         __builtin_amdgcn_global_load_lds((const unsigned*)((const char*)(gbase) + (voff)[_i]), (PG8_LAS unsigned*)(lds + (bufoff) + ldsw + _i * 8192), 16, 0, 0); } while (0)
; #define PG8_LDA(dst, b, h) do { _Pragma("unroll") for (int m = 0; m < 4; ++m) _Pragma("unroll") for (int k = 0; k < 2; ++k) dst[m][k] = *(const PG8_LAS bf16x8*)(lds + PG8_SA(b, h) + aoff + m * 2048 + k * 1024); } while (0)
; #define PG8_LDB(dst, b, h) do { _Pragma("unroll") for (int n = 0; n < 2; ++n) _Pragma("unroll") for (int k = 0; k < 2; ++k) dst[n][k] = *(const PG8_LAS bf16x8*)(lds + PG8_SB(b, h) + boff + n * 2048 + k * 1024); } while (0)
; #define PG8_MMA(ai, bj, At, Bt) do { __builtin_amdgcn_s_setprio(1); _Pragma("unroll") for (int m = 0; m < 4; ++m) _Pragma("unroll") for (int n = 0; n < 2; ++n) _Pragma("unroll") for (int k = 0; k < 2; ++k) \
;         acc[ai][bj][m][n] = __builtin_amdgcn_mfma_f32_16x16x32_bf16(Bt[n][k], At[m][k], acc[ai][bj][m][n], 0, 0, 0); __builtin_amdgcn_s_setprio(0); } while (0)
; #define PG8_WAIT_V(n) asm volatile("s_waitcnt vmcnt(" #n ")" ::: "memory")
; #define PG8_WAIT_L(n) asm volatile("s_waitcnt lgkmcnt(" #n ")" ::: "memory")
; #define PG8_BAR __builtin_amdgcn_s_barrier()
; #define PG8_SCHED __builtin_amdgcn_sched_barrier(0)
; template <class Epi, class Sched, bool ALIGN_EPI = false, bool SP2 = false, bool TILED = false>
; __device__ __forceinline__ void gemm_phase(PG8_LAS unsigned char* lds, const Gemm g, const Sched& S, const Epi& E) {
;     ...
;             PG8_LDB(B0, 0, 0); PG8_LDB(B1, 0, 1); PG8_SCHED; PG8_LDA(At, 0, 0); PG8_STAGE(PG8_SA(1, 1), a1 + hstep, voffA);
;             PG8_WAIT_V(8); PG8_WAIT_L(0); PG8_BAR; PG8_MMA(0, 0, At, B0); PG8_MMA(0, 1, At, B1); PG8_BAR; PG8_SCHED;
;             PG8_LDA(At, 0, 1); PG8_STAGE(PG8_SB(0, 0), b2, voffB); PG8_STAGE(PG8_SB(0, 1), b2 + hstep, voffB); PG8_STAGE(PG8_SA(0, 0), a2, voffA);
.LBB0_100:
	s_add_u32 s0, s50, 0xfffc0080
	s_addc_u32 s1, s51, -1
	s_add_i32 s12, 0, 0x10000
	s_cmp_eq_u32 s38, 12
	s_cselect_b32 s19, s6, s1
	s_cselect_b32 s18, s7, s0
	s_cselect_b32 s1, s8, s11
	s_cselect_b32 s0, s9, s10
	s_add_i32 s20, 0, 0x14000
	v_add_u32_e32 v44, s12, v165
	v_add_u32_e32 v162, s20, v165
	ds_read_b128 v[24:27], v44
	ds_read_b128 v[28:31], v44 offset:1024
	ds_read_b128 v[40:43], v44 offset:2048
	ds_read_b128 v[44:47], v44 offset:3072
	ds_read_b128 v[154:157], v162
	ds_read_b128 v[158:161], v162 offset:1024
	ds_read_b128 v[168:171], v162 offset:2048
	ds_read_b128 v[172:175], v162 offset:3072
	v_lshl_add_u64 v[162:163], s[50:51], 0, v[150:151]
	s_add_i32 m0, s56, 0xc000
	ds_read_b128 v[190:193], v167
	ds_read_b128 v[194:197], v167 offset:1024
	ds_read_b128 v[198:201], v167 offset:2048
	ds_read_b128 v[202:205], v167 offset:3072
	ds_read_b128 v[220:223], v167 offset:4096
	ds_read_b128 v[224:227], v167 offset:5120
	ds_read_b128 v[228:231], v167 offset:6144
	ds_read_b128 v[232:235], v167 offset:7168
	global_load_lds_dwordx4 v[162:163], off
	v_lshl_add_u64 v[162:163], s[50:51], 0, v[152:153]
	s_add_i32 m0, s56, 0xe000
	s_nop 0
	global_load_lds_dwordx4 v[162:163], off
	s_cmp_eq_u32 s38, -2
	s_cbranch_scc1 .Lmyw_0
	s_waitcnt vmcnt(8)
.Lmyw_0:
	s_waitcnt lgkmcnt(0)
	s_barrier
	s_setprio 1
	s_waitcnt lgkmcnt(0)
	v_mfma_f32_16x16x32_bf16 v[140:143], v[24:27], v[190:193], v[140:143]
	v_mfma_f32_16x16x32_bf16 v[136:139], v[40:43], v[190:193], v[136:139]
	v_mfma_f32_16x16x32_bf16 v[124:127], v[24:27], v[198:201], v[124:127]
	v_mfma_f32_16x16x32_bf16 v[120:123], v[40:43], v[198:201], v[120:123]
	v_mfma_f32_16x16x32_bf16 v[108:111], v[24:27], v[220:223], v[108:111]
	v_mfma_f32_16x16x32_bf16 v[104:107], v[40:43], v[220:223], v[104:107]
	v_mfma_f32_16x16x32_bf16 v[92:95], v[24:27], v[228:231], v[92:95]
	v_mfma_f32_16x16x32_bf16 v[88:91], v[40:43], v[228:231], v[88:91]
	v_mfma_f32_16x16x32_bf16 v[140:143], v[28:31], v[194:197], v[140:143]
	v_mfma_f32_16x16x32_bf16 v[136:139], v[44:47], v[194:197], v[136:139]
	v_mfma_f32_16x16x32_bf16 v[124:127], v[28:31], v[202:205], v[124:127]
	v_mfma_f32_16x16x32_bf16 v[120:123], v[44:47], v[202:205], v[120:123]
	v_mfma_f32_16x16x32_bf16 v[108:111], v[28:31], v[224:227], v[108:111]
	v_mfma_f32_16x16x32_bf16 v[104:107], v[44:47], v[224:227], v[104:107]
	v_mfma_f32_16x16x32_bf16 v[92:95], v[28:31], v[232:235], v[92:95]
	v_mfma_f32_16x16x32_bf16 v[88:91], v[44:47], v[232:235], v[88:91]
	s_setprio 0
	s_setprio 1
	v_mfma_f32_16x16x32_bf16 v[132:135], v[154:157], v[190:193], v[132:135]
	v_mfma_f32_16x16x32_bf16 v[128:131], v[168:171], v[190:193], v[128:131]
	v_mfma_f32_16x16x32_bf16 v[116:119], v[154:157], v[198:201], v[116:119]
	v_mfma_f32_16x16x32_bf16 v[112:115], v[168:171], v[198:201], v[112:115]
	v_mfma_f32_16x16x32_bf16 v[100:103], v[154:157], v[220:223], v[100:103]
	v_mfma_f32_16x16x32_bf16 v[96:99], v[168:171], v[220:223], v[96:99]
	v_mfma_f32_16x16x32_bf16 v[84:87], v[154:157], v[228:231], v[84:87]
	v_mfma_f32_16x16x32_bf16 v[80:83], v[168:171], v[228:231], v[80:83]
	v_mfma_f32_16x16x32_bf16 v[132:135], v[158:161], v[194:197], v[132:135]
	v_mfma_f32_16x16x32_bf16 v[128:131], v[172:175], v[194:197], v[128:131]
	v_mfma_f32_16x16x32_bf16 v[116:119], v[158:161], v[202:205], v[116:119]
	v_mfma_f32_16x16x32_bf16 v[112:115], v[172:175], v[202:205], v[112:115]
	v_mfma_f32_16x16x32_bf16 v[100:103], v[158:161], v[224:227], v[100:103]
	v_mfma_f32_16x16x32_bf16 v[96:99], v[172:175], v[224:227], v[96:99]
	v_mfma_f32_16x16x32_bf16 v[84:87], v[158:161], v[232:235], v[84:87]
	v_mfma_f32_16x16x32_bf16 v[80:83], v[172:175], v[232:235], v[80:83]
	s_setprio 0
	s_barrier
	s_add_i32 s12, s12, s53
	v_lshl_add_u64 v[162:163], s[0:1], 0, v[176:177]
	s_mov_b32 m0, s12
	ds_read_b128 v[190:193], v167 offset:16384
	ds_read_b128 v[194:197], v167 offset:17408
	ds_read_b128 v[198:201], v167 offset:18432
	ds_read_b128 v[202:205], v167 offset:19456
	ds_read_b128 v[220:223], v167 offset:20480
	ds_read_b128 v[224:227], v167 offset:21504
	ds_read_b128 v[228:231], v167 offset:22528
	ds_read_b128 v[232:235], v167 offset:23552
	global_load_lds_dwordx4 v[162:163], off
	s_add_i32 m0, s12, 0x2000
	s_add_u32 s54, s0, 0x40000
	v_lshl_add_u64 v[206:207], s[0:1], 0, v[144:145]
	s_addc_u32 s55, s1, 0
	s_add_i32 s12, s20, s53
	global_load_lds_dwordx4 v[206:207], off
	v_lshl_add_u64 v[236:237], s[54:55], 0, v[176:177]
	s_mov_b32 m0, s12
	v_lshl_add_u64 v[238:239], s[18:19], 0, v[146:147]
	global_load_lds_dwordx4 v[236:237], off
	v_lshl_add_u64 v[236:237], s[54:55], 0, v[144:145]
	s_add_i32 m0, s12, 0x2000
	s_nop 0
	global_load_lds_dwordx4 v[236:237], off
	v_lshl_add_u64 v[236:237], s[18:19], 0, v[148:149]
	s_mov_b32 m0, s56
	s_nop 0
	global_load_lds_dwordx4 v[236:237], off
	s_mov_b32 m0, s57
	s_nop 0
	global_load_lds_dwordx4 v[238:239], off
	s_cmp_eq_u32 s38, -2
	s_cbranch_scc1 .Lmyw_1
	s_waitcnt vmcnt(8)
; #define PG8_STAGE(bufoff, gbase, voff) do { _Pragma("unroll") for (int _i = 0; _i < 2; ++_i) \
;         __builtin_amdgcn_global_load_lds((const unsigned*)((const char*)(gbase) + (voff)[_i]), (PG8_LAS unsigned*)(lds + (bufoff) + ldsw + _i * 8192), 16, 0, 0); } while (0)
; #define PG8_LDA(dst, b, h) do { _Pragma("unroll") for (int m = 0; m < 4; ++m) _Pragma("unroll") for (int k = 0; k < 2; ++k) dst[m][k] = *(const PG8_LAS bf16x8*)(lds + PG8_SA(b, h) + aoff + m * 2048 + k * 1024); } while (0)
; #define PG8_LDB(dst, b, h) do { _Pragma("unroll") for (int n = 0; n < 2; ++n) _Pragma("unroll") for (int k = 0; k < 2; ++k) dst[n][k] = *(const PG8_LAS bf16x8*)(lds + PG8_SB(b, h) + boff + n * 2048 + k * 1024); } while (0)
; #define PG8_MMA(ai, bj, At, Bt) do { __builtin_amdgcn_s_setprio(1); _Pragma("unroll") for (int m = 0; m < 4; ++m) _Pragma("unroll") for (int n = 0; n < 2; ++n) _Pragma("unroll") for (int k = 0; k < 2; ++k) \
;         acc[ai][bj][m][n] = __builtin_amdgcn_mfma_f32_16x16x32_bf16(Bt[n][k], At[m][k], acc[ai][bj][m][n], 0, 0, 0); __builtin_amdgcn_s_setprio(0); } while (0)
; #define PG8_WAIT_V(n) asm volatile("s_waitcnt vmcnt(" #n ")" ::: "memory")
; #define PG8_WAIT_L(n) asm volatile("s_waitcnt lgkmcnt(" #n ")" ::: "memory")
; #define PG8_BAR __builtin_amdgcn_s_barrier()
; #define PG8_SCHED __builtin_amdgcn_sched_barrier(0)
; template <class Epi, class Sched, bool ALIGN_EPI = false, bool SP2 = false, bool TILED = false>
; __device__ __forceinline__ void gemm_phase(PG8_LAS unsigned char* lds, const Gemm g, const Sched& S, const Epi& E) {
;     ...
;             PG8_WAIT_V(8); PG8_WAIT_L(0); PG8_BAR; PG8_MMA(1, 0, At, B0); PG8_MMA(1, 1, At, B1); PG8_BAR; PG8_SCHED;
;             PG8_LDB(B0, 1, 0); PG8_LDB(B1, 1, 1); PG8_SCHED; PG8_LDA(At, 1, 0); PG8_STAGE(PG8_SA(0, 1), a2 + hstep, voffA);
;             PG8_WAIT_V(8); PG8_WAIT_L(0); PG8_BAR; PG8_MMA(0, 0, At, B0); PG8_MMA(0, 1, At, B1); PG8_BAR; PG8_SCHED;
.Lmyw_1:
	s_waitcnt lgkmcnt(0)
	s_barrier
	s_setprio 1
	s_waitcnt lgkmcnt(0)
	v_mfma_f32_16x16x32_bf16 v[76:79], v[24:27], v[190:193], v[76:79]
	v_mfma_f32_16x16x32_bf16 v[72:75], v[40:43], v[190:193], v[72:75]
	v_mfma_f32_16x16x32_bf16 v[60:63], v[24:27], v[198:201], v[60:63]
	v_mfma_f32_16x16x32_bf16 v[56:59], v[40:43], v[198:201], v[56:59]
	v_mfma_f32_16x16x32_bf16 v[36:39], v[24:27], v[220:223], v[36:39]
	v_mfma_f32_16x16x32_bf16 v[32:35], v[40:43], v[220:223], v[32:35]
	v_mfma_f32_16x16x32_bf16 v[12:15], v[24:27], v[228:231], v[12:15]
	v_mfma_f32_16x16x32_bf16 v[8:11], v[40:43], v[228:231], v[8:11]
	v_mfma_f32_16x16x32_bf16 v[76:79], v[28:31], v[194:197], v[76:79]
	v_mfma_f32_16x16x32_bf16 v[72:75], v[44:47], v[194:197], v[72:75]
	v_mfma_f32_16x16x32_bf16 v[60:63], v[28:31], v[202:205], v[60:63]
	v_mfma_f32_16x16x32_bf16 v[56:59], v[44:47], v[202:205], v[56:59]
	v_mfma_f32_16x16x32_bf16 v[36:39], v[28:31], v[224:227], v[36:39]
	v_mfma_f32_16x16x32_bf16 v[32:35], v[44:47], v[224:227], v[32:35]
	v_mfma_f32_16x16x32_bf16 v[12:15], v[28:31], v[232:235], v[12:15]
	v_mfma_f32_16x16x32_bf16 v[8:11], v[44:47], v[232:235], v[8:11]
	s_setprio 0
	s_setprio 1
	v_mfma_f32_16x16x32_bf16 v[20:23], v[154:157], v[220:223], v[20:23]
	v_mfma_f32_16x16x32_bf16 v[16:19], v[168:171], v[220:223], v[16:19]
	v_mfma_f32_16x16x32_bf16 v[4:7], v[154:157], v[228:231], v[4:7]
	v_mfma_f32_16x16x32_bf16 v[0:3], v[168:171], v[228:231], v[0:3]
	v_mfma_f32_16x16x32_bf16 v[24:27], v[154:157], v[190:193], v[68:71]
	v_mfma_f32_16x16x32_bf16 v[28:31], v[168:171], v[190:193], v[64:67]
	v_mfma_f32_16x16x32_bf16 v[40:43], v[154:157], v[198:201], v[52:55]
	v_mfma_f32_16x16x32_bf16 v[44:47], v[168:171], v[198:201], v[48:51]
	v_mfma_f32_16x16x32_bf16 v[20:23], v[158:161], v[224:227], v[20:23]
	v_mfma_f32_16x16x32_bf16 v[16:19], v[172:175], v[224:227], v[16:19]
	v_mfma_f32_16x16x32_bf16 v[4:7], v[158:161], v[232:235], v[4:7]
	v_mfma_f32_16x16x32_bf16 v[0:3], v[172:175], v[232:235], v[0:3]
	v_mfma_f32_16x16x32_bf16 v[24:27], v[158:161], v[194:197], v[24:27]
	v_mfma_f32_16x16x32_bf16 v[28:31], v[172:175], v[194:197], v[28:31]
	v_mfma_f32_16x16x32_bf16 v[40:43], v[158:161], v[202:205], v[40:43]
	v_mfma_f32_16x16x32_bf16 v[44:47], v[172:175], v[202:205], v[44:47]
	s_setprio 0
	s_barrier
	s_add_i32 s12, 0, 0x18000
	s_add_i32 s20, 0, 0x1c000
	v_add_u32_e32 v68, s12, v165
	v_add_u32_e32 v172, s20, v165
	ds_read_b128 v[48:51], v68
	ds_read_b128 v[52:55], v68 offset:1024
	ds_read_b128 v[64:67], v68 offset:2048
	ds_read_b128 v[68:71], v68 offset:3072
	ds_read_b128 v[154:157], v172
	ds_read_b128 v[158:161], v172 offset:1024
	ds_read_b128 v[168:171], v172 offset:2048
	ds_read_b128 v[172:175], v172 offset:3072
	s_add_u32 s18, s18, 0x40000
	s_addc_u32 s19, s19, 0
	s_mov_b32 m0, s64
	v_lshl_add_u64 v[240:241], s[18:19], 0, v[148:149]
	ds_read_b128 v[190:193], v167 offset:32768
	ds_read_b128 v[194:197], v167 offset:33792
	ds_read_b128 v[198:201], v167 offset:34816
	ds_read_b128 v[202:205], v167 offset:35840
	ds_read_b128 v[220:223], v167 offset:36864
	ds_read_b128 v[224:227], v167 offset:37888
	ds_read_b128 v[228:231], v167 offset:38912
	ds_read_b128 v[232:235], v167 offset:39936
	global_load_lds_dwordx4 v[240:241], off
	v_lshl_add_u64 v[240:241], s[18:19], 0, v[146:147]
	s_mov_b32 m0, s65
	s_nop 0
	global_load_lds_dwordx4 v[240:241], off
	s_waitcnt vmcnt(8)
	s_waitcnt lgkmcnt(0)
	s_barrier
	s_setprio 1
	s_waitcnt lgkmcnt(0)
	v_mfma_f32_16x16x32_bf16 v[140:143], v[48:51], v[190:193], v[140:143]
	v_mfma_f32_16x16x32_bf16 v[136:139], v[64:67], v[190:193], v[136:139]
	v_mfma_f32_16x16x32_bf16 v[124:127], v[48:51], v[198:201], v[124:127]
	v_mfma_f32_16x16x32_bf16 v[120:123], v[64:67], v[198:201], v[120:123]
	v_mfma_f32_16x16x32_bf16 v[108:111], v[48:51], v[220:223], v[108:111]
	v_mfma_f32_16x16x32_bf16 v[104:107], v[64:67], v[220:223], v[104:107]
	v_mfma_f32_16x16x32_bf16 v[92:95], v[48:51], v[228:231], v[92:95]
	v_mfma_f32_16x16x32_bf16 v[88:91], v[64:67], v[228:231], v[88:91]
	v_mfma_f32_16x16x32_bf16 v[140:143], v[52:55], v[194:197], v[140:143]
	v_mfma_f32_16x16x32_bf16 v[136:139], v[68:71], v[194:197], v[136:139]
	v_mfma_f32_16x16x32_bf16 v[124:127], v[52:55], v[202:205], v[124:127]
	v_mfma_f32_16x16x32_bf16 v[120:123], v[68:71], v[202:205], v[120:123]
	v_mfma_f32_16x16x32_bf16 v[108:111], v[52:55], v[224:227], v[108:111]
	v_mfma_f32_16x16x32_bf16 v[104:107], v[68:71], v[224:227], v[104:107]
	v_mfma_f32_16x16x32_bf16 v[92:95], v[52:55], v[232:235], v[92:95]
	v_mfma_f32_16x16x32_bf16 v[88:91], v[68:71], v[232:235], v[88:91]
	s_setprio 0
	s_setprio 1
	v_mfma_f32_16x16x32_bf16 v[132:135], v[154:157], v[190:193], v[132:135]
	v_mfma_f32_16x16x32_bf16 v[128:131], v[168:171], v[190:193], v[128:131]
	v_mfma_f32_16x16x32_bf16 v[116:119], v[154:157], v[198:201], v[116:119]
	v_mfma_f32_16x16x32_bf16 v[112:115], v[168:171], v[198:201], v[112:115]
	v_mfma_f32_16x16x32_bf16 v[100:103], v[154:157], v[220:223], v[100:103]
	v_mfma_f32_16x16x32_bf16 v[96:99], v[168:171], v[220:223], v[96:99]
	v_mfma_f32_16x16x32_bf16 v[84:87], v[154:157], v[228:231], v[84:87]
	v_mfma_f32_16x16x32_bf16 v[80:83], v[168:171], v[228:231], v[80:83]
	v_mfma_f32_16x16x32_bf16 v[132:135], v[158:161], v[194:197], v[132:135]
	v_mfma_f32_16x16x32_bf16 v[128:131], v[172:175], v[194:197], v[128:131]
	v_mfma_f32_16x16x32_bf16 v[116:119], v[158:161], v[202:205], v[116:119]
	v_mfma_f32_16x16x32_bf16 v[112:115], v[172:175], v[202:205], v[112:115]
	v_mfma_f32_16x16x32_bf16 v[100:103], v[158:161], v[224:227], v[100:103]
	v_mfma_f32_16x16x32_bf16 v[96:99], v[172:175], v[224:227], v[96:99]
	v_mfma_f32_16x16x32_bf16 v[84:87], v[158:161], v[232:235], v[84:87]
	v_mfma_f32_16x16x32_bf16 v[80:83], v[172:175], v[232:235], v[80:83]
	s_setprio 0
	s_barrier
; #define PG8_STAGE(bufoff, gbase, voff) do { _Pragma("unroll") for (int _i = 0; _i < 2; ++_i) \
;         __builtin_amdgcn_global_load_lds((const unsigned*)((const char*)(gbase) + (voff)[_i]), (PG8_LAS unsigned*)(lds + (bufoff) + ldsw + _i * 8192), 16, 0, 0); } while (0)
; #define PG8_LDA(dst, b, h) do { _Pragma("unroll") for (int m = 0; m < 4; ++m) _Pragma("unroll") for (int k = 0; k < 2; ++k) dst[m][k] = *(const PG8_LAS bf16x8*)(lds + PG8_SA(b, h) + aoff + m * 2048 + k * 1024); } while (0)
; #define PG8_MMA(ai, bj, At, Bt) do { __builtin_amdgcn_s_setprio(1); _Pragma("unroll") for (int m = 0; m < 4; ++m) _Pragma("unroll") for (int n = 0; n < 2; ++n) _Pragma("unroll") for (int k = 0; k < 2; ++k) \
;         acc[ai][bj][m][n] = __builtin_amdgcn_mfma_f32_16x16x32_bf16(Bt[n][k], At[m][k], acc[ai][bj][m][n], 0, 0, 0); __builtin_amdgcn_s_setprio(0); } while (0)
; #define PG8_WAIT_V(n) asm volatile("s_waitcnt vmcnt(" #n ")" ::: "memory")
; #define PG8_WAIT_L(n) asm volatile("s_waitcnt lgkmcnt(" #n ")" ::: "memory")
; #define PG8_BAR __builtin_amdgcn_s_barrier()
; #define PG8_SCHED __builtin_amdgcn_sched_barrier(0)
; template <class Epi, class Sched, bool ALIGN_EPI = false, bool SP2 = false, bool TILED = false>
; __device__ __forceinline__ void gemm_phase(PG8_LAS unsigned char* lds, const Gemm g, const Sched& S, const Epi& E) {
;     ...
;             PG8_LDA(At, 1, 1); PG8_STAGE(PG8_SB(1, 0), b3, voffB); PG8_STAGE(PG8_SB(1, 1), b3 + hstep, voffB); PG8_STAGE(PG8_SA(1, 0), a3, voffA);
;             PG8_WAIT_V(8); PG8_WAIT_L(0); PG8_BAR; PG8_MMA(1, 0, At, B0); PG8_MMA(1, 1, At, B1); PG8_BAR; PG8_SCHED;
	s_add_i32 s12, s12, s53
	v_lshl_add_u64 v[162:163], v[162:163], 0, s[26:27]
	s_mov_b32 m0, s12
	ds_read_b128 v[190:193], v167 offset:49152
	ds_read_b128 v[194:197], v167 offset:50176
	ds_read_b128 v[198:201], v167 offset:51200
	ds_read_b128 v[202:205], v167 offset:52224
	ds_read_b128 v[220:223], v167 offset:53248
	ds_read_b128 v[224:227], v167 offset:54272
	ds_read_b128 v[228:231], v167 offset:55296
	ds_read_b128 v[232:235], v167 offset:56320
	global_load_lds_dwordx4 v[162:163], off
	s_add_i32 m0, s12, 0x2000
	s_add_u32 s0, s0, 0x40080
	v_lshl_add_u64 v[162:163], v[206:207], 0, s[26:27]
	s_addc_u32 s1, s1, 0
	s_add_i32 s12, s20, s53
	global_load_lds_dwordx4 v[162:163], off
	v_lshl_add_u64 v[162:163], s[0:1], 0, v[176:177]
	s_mov_b32 m0, s12
	s_nop 0
	global_load_lds_dwordx4 v[162:163], off
	v_lshl_add_u64 v[162:163], s[0:1], 0, v[144:145]
	s_add_i32 m0, s12, 0x2000
	s_nop 0
	global_load_lds_dwordx4 v[162:163], off
	v_lshl_add_u64 v[162:163], v[236:237], 0, s[26:27]
	s_mov_b32 m0, s66
	s_nop 0
	global_load_lds_dwordx4 v[162:163], off
	v_lshl_add_u64 v[162:163], v[238:239], 0, s[26:27]
	s_mov_b32 m0, s67
	s_nop 0
	global_load_lds_dwordx4 v[162:163], off
	s_waitcnt vmcnt(8)
	s_waitcnt lgkmcnt(0)
	s_barrier
	s_setprio 1
	s_waitcnt lgkmcnt(0)
	v_mfma_f32_16x16x32_bf16 v[76:79], v[48:51], v[190:193], v[76:79]
	v_mfma_f32_16x16x32_bf16 v[72:75], v[64:67], v[190:193], v[72:75]
	v_mfma_f32_16x16x32_bf16 v[60:63], v[48:51], v[198:201], v[60:63]
	v_mfma_f32_16x16x32_bf16 v[56:59], v[64:67], v[198:201], v[56:59]
	v_mfma_f32_16x16x32_bf16 v[36:39], v[48:51], v[220:223], v[36:39]
	v_mfma_f32_16x16x32_bf16 v[32:35], v[64:67], v[220:223], v[32:35]
	v_mfma_f32_16x16x32_bf16 v[12:15], v[48:51], v[228:231], v[12:15]
	v_mfma_f32_16x16x32_bf16 v[8:11], v[64:67], v[228:231], v[8:11]
	v_mfma_f32_16x16x32_bf16 v[76:79], v[52:55], v[194:197], v[76:79]
	v_mfma_f32_16x16x32_bf16 v[72:75], v[68:71], v[194:197], v[72:75]
	v_mfma_f32_16x16x32_bf16 v[60:63], v[52:55], v[202:205], v[60:63]
	v_mfma_f32_16x16x32_bf16 v[56:59], v[68:71], v[202:205], v[56:59]
	v_mfma_f32_16x16x32_bf16 v[36:39], v[52:55], v[224:227], v[36:39]
	v_mfma_f32_16x16x32_bf16 v[32:35], v[68:71], v[224:227], v[32:35]
	v_mfma_f32_16x16x32_bf16 v[12:15], v[52:55], v[232:235], v[12:15]
	v_mfma_f32_16x16x32_bf16 v[8:11], v[68:71], v[232:235], v[8:11]
	s_setprio 0
	s_setprio 1
	v_mfma_f32_16x16x32_bf16 v[24:27], v[154:157], v[190:193], v[24:27]
	v_mfma_f32_16x16x32_bf16 v[68:71], v[158:161], v[194:197], v[24:27]
	v_mfma_f32_16x16x32_bf16 v[24:27], v[168:171], v[190:193], v[28:31]
	v_mfma_f32_16x16x32_bf16 v[64:67], v[172:175], v[194:197], v[24:27]
	v_mfma_f32_16x16x32_bf16 v[24:27], v[154:157], v[198:201], v[40:43]
	v_mfma_f32_16x16x32_bf16 v[52:55], v[158:161], v[202:205], v[24:27]
	v_mfma_f32_16x16x32_bf16 v[24:27], v[168:171], v[198:201], v[44:47]
	v_mfma_f32_16x16x32_bf16 v[20:23], v[154:157], v[220:223], v[20:23]
	v_mfma_f32_16x16x32_bf16 v[16:19], v[168:171], v[220:223], v[16:19]
	v_mfma_f32_16x16x32_bf16 v[4:7], v[154:157], v[228:231], v[4:7]
	v_mfma_f32_16x16x32_bf16 v[0:3], v[168:171], v[228:231], v[0:3]
	v_mfma_f32_16x16x32_bf16 v[48:51], v[172:175], v[202:205], v[24:27]
	v_mfma_f32_16x16x32_bf16 v[20:23], v[158:161], v[224:227], v[20:23]
	v_mfma_f32_16x16x32_bf16 v[16:19], v[172:175], v[224:227], v[16:19]
	v_mfma_f32_16x16x32_bf16 v[4:7], v[158:161], v[232:235], v[4:7]
	v_mfma_f32_16x16x32_bf16 v[0:3], v[172:175], v[232:235], v[0:3]
	s_setprio 0
	s_barrier
	s_add_i32 s38, s38, 2
	s_add_u32 s50, s50, 0x100
	s_addc_u32 s51, s51, 0
	s_add_u32 s10, s10, 0x100
	s_addc_u32 s11, s11, 0
	s_cmp_gt_u32 s38, 13
	s_cbranch_scc0 .LBB0_100
	s_and_b64 vcc, exec, s[16:17]
	s_cbranch_vccz .LBB0_103
	s_barrier

; #define PG8_STAGE(bufoff, gbase, voff) do { _Pragma("unroll") for (int _i = 0; _i < 2; ++_i) \
;         __builtin_amdgcn_global_load_lds((const unsigned*)((const char*)(gbase) + (voff)[_i]), (PG8_LAS unsigned*)(lds + (bufoff) + ldsw + _i * 8192), 16, 0, 0); } while (0)
; #define PG8_WAIT_V(n) asm volatile("s_waitcnt vmcnt(" #n ")" ::: "memory")
; #define PG8_BAR __builtin_amdgcn_s_barrier()
; template <class Epi, class Sched, bool ALIGN_EPI = false, bool SP2 = false, bool TILED = false>
; __device__ __forceinline__ void gemm_phase(PG8_LAS unsigned char* lds, const Gemm g, const Sched& S, const Epi& E) {
;     ...
;     for (int i = 0; i < 2; ++i) { int R, C; stage_rc(tid * 16 + i * 8192, R, C); const int Rb = Epi::PERM ? ((R & ~31) + perm32(R & 31)) : R;
;         const int rs = TILED ? BK : K; voffA[i] = (unsigned)(R * rs + C) * 2u; voffB[i] = (unsigned)(Rb * rs + C) * 2u; }
;     const size_t kstep = TILED ? (size_t)(BM * BK * 2) : (size_t)(BK * 2);
;     const size_t hstep = TILED ? (size_t)(HALF * BK * 2) : (size_t)HALF * K * 2;
;     const size_t tstep = TILED ? (size_t)(K / BK) * (BM * BK * 2) : 2 * hstep;
;     const unsigned ldsw = (unsigned)wid * 1024u;
;     const int aoff = lds_byte(wr * 64 + fr, fq * 8), boff = lds_byte(wc * 32 + fr, fq * 8);
;     ...
;     Unit cur, nxt; int ui = 0;
;     if (!S.next(0, cur)) return;
;     f32x4 acc[2][2][4][2];
; #pragma unroll
;     for (int a = 0; a < 2; ++a)
; #pragma unroll
;         for (int b = 0; b < 2; ++b)
; #pragma unroll
;             for (int m = 0; m < 4; ++m)
; #pragma unroll
;                 for (int n = 0; n < 2; ++n) acc[a][b][m][n] = (f32x4){0.f, 0.f, 0.f, 0.f};
;     bf16x8 At[4][2], B0[2][2], B1[2][2];
;     const char* cA = (const char*)g.A + (size_t)cur.pm * tstep; const char* cB = (const char*)g.Bt + (size_t)cur.pn * tstep;
;     S.a_ready(cur);
;     if constexpr (SP2) {
;         PG8_STAGE(PG8_SB(0, 0), cB, voffB); PG8_STAGE(PG8_SB(0, 1), cB + hstep, voffB); PG8_STAGE(PG8_SA(0, 0), cA, voffA); PG8_STAGE(PG8_SA(0, 1), cA + hstep, voffA);
;         if (wr == 1) PG8_BAR;
;         PG8_WAIT_V(2); PG8_BAR;
;         PG8_STAGE(PG8_SB(1, 0), cB + kstep, voffB); PG8_STAGE(PG8_SA(1, 0), cA + kstep, voffA); PG8_STAGE(PG8_SB(1, 1), cB + hstep + kstep, voffB);
;         PG8_WAIT_V(6); PG8_BAR;
.LBB0_634:
	v_readlane_b32 s6, v250, 41
	v_bfe_u32 v153, v6, 4, 2
	s_lshl_b32 s1, s1, 5
	v_readlane_b32 s7, v250, 42
	v_and_b32_e32 v152, 15, v6
	v_lshlrev_b32_e32 v7, 4, v153
	v_lshlrev_b32_e32 v6, 2, v6
	s_and_b32 s67, s1, 0x60
	v_lshl_add_u64 v[8:9], s[6:7], 0, v[176:177]
	v_mov_b32_e32 v137, v177
	v_readlane_b32 s14, v250, 37
	s_lshl_b32 s66, s4, 6
	v_lshl_or_b32 v7, v152, 6, v7
	s_lshl_b32 s4, s4, 13
	v_and_b32_e32 v6, 32, v6
	s_lshl_b32 s1, s67, 7
	v_lshl_add_u64 v[10:11], s[6:7], 0, v[136:137]
	v_mov_b32_e32 v141, v177
	v_readlane_b32 s15, v250, 38
	v_bitop3_b32 v16, v7, s4, v6 bitop3:0xde
	v_bitop3_b32 v155, v7, s1, v6 bitop3:0xde
	s_add_i32 m0, s38, 0x18000
	v_lshl_add_u64 v[6:7], v[8:9], 0, s[26:27]
	s_waitcnt vmcnt(0)
	v_lshl_add_u64 v[12:13], s[14:15], 0, v[140:141]
	v_mov_b32_e32 v139, v177
	s_waitcnt vmcnt(2)
	s_barrier
	global_load_lds_dwordx4 v[6:7], off
	v_lshl_add_u64 v[6:7], v[10:11], 0, s[26:27]
	s_add_i32 m0, s38, 0x1a000
	s_add_i32 s72, s38, 0x8000
	v_lshl_add_u64 v[14:15], s[14:15], 0, v[138:139]
	global_load_lds_dwordx4 v[6:7], off
	v_lshl_add_u64 v[6:7], v[12:13], 0, s[26:27]
	s_mov_b32 m0, s72
	s_add_i32 s73, s38, 0xa000
	v_readlane_b32 s4, v250, 43
	global_load_lds_dwordx4 v[6:7], off
	v_lshl_add_u64 v[6:7], v[14:15], 0, s[26:27]
	s_mov_b32 m0, s73
	v_readlane_b32 s5, v250, 44
	global_load_lds_dwordx4 v[6:7], off
	s_add_i32 m0, s38, 0x1c000
	v_lshl_add_u64 v[6:7], s[4:5], 0, v[176:177]
	global_load_lds_dwordx4 v[6:7], off
	v_lshl_add_u64 v[6:7], s[4:5], 0, v[136:137]
	s_add_i32 m0, s38, 0x1e000
	s_cmpk_lt_u32 s0, 0x100
	global_load_lds_dwordx4 v[6:7], off
	v_lshlrev_b32_e32 v6, 14, v4
	v_and_b32_e32 v6, 0xffff8000, v6
	v_lshl_add_u32 v3, v3, 11, v6
	v_and_b32_e32 v4, 1, v4
	v_lshl_or_b32 v3, v4, 6, v3
	v_lshl_add_u32 v142, v5, 1, v3
	v_lshlrev_b32_e32 v3, 14, v0
	v_and_b32_e32 v3, 0xffff8000, v3
	s_waitcnt vmcnt(0)
	v_lshl_add_u32 v1, v1, 11, v3
	v_and_b32_e32 v0, 1, v0
	v_readlane_b32 s0, v249, 19
	v_lshl_or_b32 v0, v0, 6, v1
	v_readlane_b32 s1, v249, 20
	v_or_b32_e32 v154, s66, v152
	s_cselect_b64 s[46:47], -1, 0
	v_lshl_or_b32 v156, v153, 3, s67
	v_mov_b32_e32 v143, v177
	v_lshl_add_u32 v144, v2, 1, v0
	v_mov_b32_e32 v145, v177
	s_mov_b32 s76, 0
	v_add_u32_e32 v157, 0, v16
	v_readlane_b32 s4, v250, 31
	s_mov_b32 s5, s0
	s_mov_b64 s[0:1], s[6:7]
	v_readlane_b32 s20, v250, 33
	v_readlane_b32 s21, v250, 34
	s_barrier
	s_branch .LBB0_637

; #define PG8_STAGE(bufoff, gbase, voff) do { _Pragma("unroll") for (int _i = 0; _i < 2; ++_i) \
;         __builtin_amdgcn_global_load_lds((const unsigned*)((const char*)(gbase) + (voff)[_i]), (PG8_LAS unsigned*)(lds + (bufoff) + ldsw + _i * 8192), 16, 0, 0); } while (0)
; #define PG8_LDA(dst, b, h) do { _Pragma("unroll") for (int m = 0; m < 4; ++m) _Pragma("unroll") for (int k = 0; k < 2; ++k) dst[m][k] = *(const PG8_LAS bf16x8*)(lds + PG8_SA(b, h) + aoff + m * 2048 + k * 1024); } while (0)
; #define PG8_LDB(dst, b, h) do { _Pragma("unroll") for (int n = 0; n < 2; ++n) _Pragma("unroll") for (int k = 0; k < 2; ++k) dst[n][k] = *(const PG8_LAS bf16x8*)(lds + PG8_SB(b, h) + boff + n * 2048 + k * 1024); } while (0)
; #define PG8_MMA(ai, bj, At, Bt) do { __builtin_amdgcn_s_setprio(1); _Pragma("unroll") for (int m = 0; m < 4; ++m) _Pragma("unroll") for (int n = 0; n < 2; ++n) _Pragma("unroll") for (int k = 0; k < 2; ++k) \
;         acc[ai][bj][m][n] = __builtin_amdgcn_mfma_f32_16x16x32_bf16(Bt[n][k], At[m][k], acc[ai][bj][m][n], 0, 0, 0); __builtin_amdgcn_s_setprio(0); } while (0)
; #define PG8_WAIT_V(n) asm volatile("s_waitcnt vmcnt(" #n ")" ::: "memory")
; #define PG8_WAIT_L(n) asm volatile("s_waitcnt lgkmcnt(" #n ")" ::: "memory")
; #define PG8_BAR __builtin_amdgcn_s_barrier()
; #define PG8_SCHED __builtin_amdgcn_sched_barrier(0)
; template <class Epi, class Sched, bool ALIGN_EPI = false, bool SP2 = false, bool TILED = false>
; __device__ __forceinline__ void gemm_phase(PG8_LAS unsigned char* lds, const Gemm g, const Sched& S, const Epi& E) {
;     ...
;             PG8_LDB(B0, 0, 0); PG8_LDB(B1, 0, 1); PG8_SCHED; PG8_LDA(At, 0, 0); PG8_STAGE(PG8_SA(1, 1), a1 + hstep, voffA);
;             PG8_WAIT_V(8); PG8_WAIT_L(0); PG8_BAR; PG8_MMA(0, 0, At, B0); PG8_MMA(0, 1, At, B1); PG8_BAR; PG8_SCHED;
;             PG8_LDA(At, 0, 1); PG8_STAGE(PG8_SB(0, 0), b2, voffB); PG8_STAGE(PG8_SB(0, 1), b2 + hstep, voffB); PG8_STAGE(PG8_SA(0, 0), a2, voffA);
.LBB0_644:
	s_add_u32 s0, s14, s16
	s_addc_u32 s1, s15, s17
	s_add_u32 s0, s0, 0x100
	s_addc_u32 s1, s1, 0
	s_add_u32 s4, s94, s16
	s_addc_u32 s5, s95, s17
	s_cmpk_eq_i32 s16, 0x700
	s_cselect_b32 s19, s51, s1
	s_cselect_b32 s18, s77, s0
	s_cselect_b32 s1, s79, s5
	s_cselect_b32 s0, s80, s4
	s_add_i32 s4, 0, 0x10000
	v_add_u32_e32 v150, s4, v155
	s_add_i32 s6, 0, 0x14000
	ds_read_b128 v[128:131], v150
	ds_read_b128 v[132:135], v150 offset:1024
	ds_read_b128 v[158:161], v150 offset:2048
	ds_read_b128 v[162:165], v150 offset:3072
	v_add_u32_e32 v150, s6, v155
	ds_read_b128 v[166:169], v150
	ds_read_b128 v[170:173], v150 offset:1024
	ds_read_b128 v[190:193], v150 offset:2048
	ds_read_b128 v[194:197], v150 offset:3072
	v_lshl_add_u64 v[150:151], v[146:147], 0, s[16:17]
	s_add_i32 m0, s38, 0xc000
	ds_read_b128 v[198:201], v157
	ds_read_b128 v[202:205], v157 offset:1024
	ds_read_b128 v[220:223], v157 offset:2048
	ds_read_b128 v[224:227], v157 offset:3072
	ds_read_b128 v[228:231], v157 offset:4096
	ds_read_b128 v[232:235], v157 offset:5120
	ds_read_b128 v[236:239], v157 offset:6144
	ds_read_b128 v[240:243], v157 offset:7168
	global_load_lds_dwordx4 v[150:151], off
	v_lshl_add_u64 v[150:151], v[148:149], 0, s[16:17]
	s_add_i32 m0, s38, 0xe000
	s_nop 0
	global_load_lds_dwordx4 v[150:151], off
	s_cmp_eq_u32 s40, -2
	s_cbranch_scc1 .Lmyw_2
	s_waitcnt vmcnt(8)
.Lmyw_2:
	s_waitcnt lgkmcnt(0)
	s_barrier
	s_setprio 1
	s_waitcnt lgkmcnt(0)
	v_mfma_f32_16x16x32_bf16 v[124:127], v[128:131], v[198:201], v[124:127]
	v_mfma_f32_16x16x32_bf16 v[120:123], v[158:161], v[198:201], v[120:123]
	v_mfma_f32_16x16x32_bf16 v[108:111], v[128:131], v[220:223], v[108:111]
	v_mfma_f32_16x16x32_bf16 v[104:107], v[158:161], v[220:223], v[104:107]
	v_mfma_f32_16x16x32_bf16 v[92:95], v[128:131], v[228:231], v[92:95]
	v_mfma_f32_16x16x32_bf16 v[88:91], v[158:161], v[228:231], v[88:91]
	v_mfma_f32_16x16x32_bf16 v[76:79], v[128:131], v[236:239], v[76:79]
	v_mfma_f32_16x16x32_bf16 v[72:75], v[158:161], v[236:239], v[72:75]
	v_mfma_f32_16x16x32_bf16 v[124:127], v[132:135], v[202:205], v[124:127]
	v_mfma_f32_16x16x32_bf16 v[120:123], v[162:165], v[202:205], v[120:123]
	v_mfma_f32_16x16x32_bf16 v[108:111], v[132:135], v[224:227], v[108:111]
	v_mfma_f32_16x16x32_bf16 v[104:107], v[162:165], v[224:227], v[104:107]
	v_mfma_f32_16x16x32_bf16 v[92:95], v[132:135], v[232:235], v[92:95]
	v_mfma_f32_16x16x32_bf16 v[88:91], v[162:165], v[232:235], v[88:91]
	v_mfma_f32_16x16x32_bf16 v[76:79], v[132:135], v[240:243], v[76:79]
	v_mfma_f32_16x16x32_bf16 v[72:75], v[162:165], v[240:243], v[72:75]
	s_setprio 0
	s_setprio 1
	v_mfma_f32_16x16x32_bf16 v[116:119], v[166:169], v[198:201], v[116:119]
	v_mfma_f32_16x16x32_bf16 v[112:115], v[190:193], v[198:201], v[112:115]
	v_mfma_f32_16x16x32_bf16 v[100:103], v[166:169], v[220:223], v[100:103]
	v_mfma_f32_16x16x32_bf16 v[96:99], v[190:193], v[220:223], v[96:99]
	v_mfma_f32_16x16x32_bf16 v[84:87], v[166:169], v[228:231], v[84:87]
	v_mfma_f32_16x16x32_bf16 v[80:83], v[190:193], v[228:231], v[80:83]
	v_mfma_f32_16x16x32_bf16 v[68:71], v[166:169], v[236:239], v[68:71]
	v_mfma_f32_16x16x32_bf16 v[64:67], v[190:193], v[236:239], v[64:67]
	v_mfma_f32_16x16x32_bf16 v[116:119], v[170:173], v[202:205], v[116:119]
	v_mfma_f32_16x16x32_bf16 v[112:115], v[194:197], v[202:205], v[112:115]
	v_mfma_f32_16x16x32_bf16 v[100:103], v[170:173], v[224:227], v[100:103]
	v_mfma_f32_16x16x32_bf16 v[96:99], v[194:197], v[224:227], v[96:99]
	v_mfma_f32_16x16x32_bf16 v[84:87], v[170:173], v[232:235], v[84:87]
	v_mfma_f32_16x16x32_bf16 v[80:83], v[194:197], v[232:235], v[80:83]
	v_mfma_f32_16x16x32_bf16 v[68:71], v[170:173], v[240:243], v[68:71]
	v_mfma_f32_16x16x32_bf16 v[64:67], v[194:197], v[240:243], v[64:67]
	s_setprio 0
	s_barrier
	s_add_i32 s4, s4, s34
	v_lshl_add_u64 v[150:151], s[0:1], 0, v[176:177]
	s_mov_b32 m0, s4
	ds_read_b128 v[198:201], v157 offset:16384
	ds_read_b128 v[202:205], v157 offset:17408
	ds_read_b128 v[220:223], v157 offset:18432
	ds_read_b128 v[224:227], v157 offset:19456
	ds_read_b128 v[228:231], v157 offset:20480
	ds_read_b128 v[232:235], v157 offset:21504
	ds_read_b128 v[236:239], v157 offset:22528
	ds_read_b128 v[240:243], v157 offset:23552
	global_load_lds_dwordx4 v[150:151], off
	s_add_i32 m0, s4, 0x2000
	s_add_u32 s4, s0, 0x40000
	v_lshl_add_u64 v[174:175], s[0:1], 0, v[136:137]
	s_addc_u32 s5, s1, 0
	s_add_i32 s6, s6, s34
	global_load_lds_dwordx4 v[174:175], off
	v_lshl_add_u64 v[206:207], s[4:5], 0, v[176:177]
	s_mov_b32 m0, s6
	v_lshl_add_u64 v[244:245], s[18:19], 0, v[138:139]
	global_load_lds_dwordx4 v[206:207], off
	v_lshl_add_u64 v[206:207], s[4:5], 0, v[136:137]
	s_add_i32 m0, s6, 0x2000
	s_nop 0
	global_load_lds_dwordx4 v[206:207], off
	v_lshl_add_u64 v[206:207], s[18:19], 0, v[140:141]
	s_mov_b32 m0, s38
	s_nop 0
	global_load_lds_dwordx4 v[206:207], off
	s_mov_b32 m0, s39
	s_nop 0
	global_load_lds_dwordx4 v[244:245], off
	s_cmp_eq_u32 s40, -2
	s_cbranch_scc1 .Lmyw_3
	s_waitcnt vmcnt(8)
; #define PG8_STAGE(bufoff, gbase, voff) do { _Pragma("unroll") for (int _i = 0; _i < 2; ++_i) \
;         __builtin_amdgcn_global_load_lds((const unsigned*)((const char*)(gbase) + (voff)[_i]), (PG8_LAS unsigned*)(lds + (bufoff) + ldsw + _i * 8192), 16, 0, 0); } while (0)
; #define PG8_LDA(dst, b, h) do { _Pragma("unroll") for (int m = 0; m < 4; ++m) _Pragma("unroll") for (int k = 0; k < 2; ++k) dst[m][k] = *(const PG8_LAS bf16x8*)(lds + PG8_SA(b, h) + aoff + m * 2048 + k * 1024); } while (0)
; #define PG8_LDB(dst, b, h) do { _Pragma("unroll") for (int n = 0; n < 2; ++n) _Pragma("unroll") for (int k = 0; k < 2; ++k) dst[n][k] = *(const PG8_LAS bf16x8*)(lds + PG8_SB(b, h) + boff + n * 2048 + k * 1024); } while (0)
; #define PG8_MMA(ai, bj, At, Bt) do { __builtin_amdgcn_s_setprio(1); _Pragma("unroll") for (int m = 0; m < 4; ++m) _Pragma("unroll") for (int n = 0; n < 2; ++n) _Pragma("unroll") for (int k = 0; k < 2; ++k) \
;         acc[ai][bj][m][n] = __builtin_amdgcn_mfma_f32_16x16x32_bf16(Bt[n][k], At[m][k], acc[ai][bj][m][n], 0, 0, 0); __builtin_amdgcn_s_setprio(0); } while (0)
; #define PG8_WAIT_V(n) asm volatile("s_waitcnt vmcnt(" #n ")" ::: "memory")
; #define PG8_WAIT_L(n) asm volatile("s_waitcnt lgkmcnt(" #n ")" ::: "memory")
; #define PG8_BAR __builtin_amdgcn_s_barrier()
; #define PG8_SCHED __builtin_amdgcn_sched_barrier(0)
; template <class Epi, class Sched, bool ALIGN_EPI = false, bool SP2 = false, bool TILED = false>
; __device__ __forceinline__ void gemm_phase(PG8_LAS unsigned char* lds, const Gemm g, const Sched& S, const Epi& E) {
;     ...
;             PG8_WAIT_V(8); PG8_WAIT_L(0); PG8_BAR; PG8_MMA(1, 0, At, B0); PG8_MMA(1, 1, At, B1); PG8_BAR; PG8_SCHED;
;             PG8_LDB(B0, 1, 0); PG8_LDB(B1, 1, 1); PG8_SCHED; PG8_LDA(At, 1, 0); PG8_STAGE(PG8_SA(0, 1), a2 + hstep, voffA);
;             PG8_WAIT_V(8); PG8_WAIT_L(0); PG8_BAR; PG8_MMA(0, 0, At, B0); PG8_MMA(0, 1, At, B1); PG8_BAR; PG8_SCHED;
.Lmyw_3:
	s_waitcnt lgkmcnt(0)
	s_barrier
	s_setprio 1
	s_waitcnt lgkmcnt(0)
	v_mfma_f32_16x16x32_bf16 v[60:63], v[128:131], v[198:201], v[60:63]
	v_mfma_f32_16x16x32_bf16 v[56:59], v[158:161], v[198:201], v[56:59]
	v_mfma_f32_16x16x32_bf16 v[44:47], v[128:131], v[220:223], v[44:47]
	v_mfma_f32_16x16x32_bf16 v[40:43], v[158:161], v[220:223], v[40:43]
	v_mfma_f32_16x16x32_bf16 v[28:31], v[128:131], v[228:231], v[28:31]
	v_mfma_f32_16x16x32_bf16 v[24:27], v[158:161], v[228:231], v[24:27]
	v_mfma_f32_16x16x32_bf16 v[12:15], v[128:131], v[236:239], v[12:15]
	v_mfma_f32_16x16x32_bf16 v[8:11], v[158:161], v[236:239], v[8:11]
	v_mfma_f32_16x16x32_bf16 v[60:63], v[132:135], v[202:205], v[60:63]
	v_mfma_f32_16x16x32_bf16 v[56:59], v[162:165], v[202:205], v[56:59]
	v_mfma_f32_16x16x32_bf16 v[44:47], v[132:135], v[224:227], v[44:47]
	v_mfma_f32_16x16x32_bf16 v[40:43], v[162:165], v[224:227], v[40:43]
	v_mfma_f32_16x16x32_bf16 v[28:31], v[132:135], v[232:235], v[28:31]
	v_mfma_f32_16x16x32_bf16 v[24:27], v[162:165], v[232:235], v[24:27]
	v_mfma_f32_16x16x32_bf16 v[12:15], v[132:135], v[240:243], v[12:15]
	v_mfma_f32_16x16x32_bf16 v[8:11], v[162:165], v[240:243], v[8:11]
	s_setprio 0
	s_setprio 1
	v_mfma_f32_16x16x32_bf16 v[52:55], v[166:169], v[198:201], v[52:55]
	v_mfma_f32_16x16x32_bf16 v[48:51], v[190:193], v[198:201], v[48:51]
	v_mfma_f32_16x16x32_bf16 v[36:39], v[166:169], v[220:223], v[36:39]
	v_mfma_f32_16x16x32_bf16 v[32:35], v[190:193], v[220:223], v[32:35]
	v_mfma_f32_16x16x32_bf16 v[20:23], v[166:169], v[228:231], v[20:23]
	v_mfma_f32_16x16x32_bf16 v[16:19], v[190:193], v[228:231], v[16:19]
	v_mfma_f32_16x16x32_bf16 v[4:7], v[166:169], v[236:239], v[4:7]
	v_mfma_f32_16x16x32_bf16 v[0:3], v[190:193], v[236:239], v[0:3]
	v_mfma_f32_16x16x32_bf16 v[52:55], v[170:173], v[202:205], v[52:55]
	v_mfma_f32_16x16x32_bf16 v[48:51], v[194:197], v[202:205], v[48:51]
	v_mfma_f32_16x16x32_bf16 v[36:39], v[170:173], v[224:227], v[36:39]
	v_mfma_f32_16x16x32_bf16 v[32:35], v[194:197], v[224:227], v[32:35]
	v_mfma_f32_16x16x32_bf16 v[20:23], v[170:173], v[232:235], v[20:23]
	v_mfma_f32_16x16x32_bf16 v[16:19], v[194:197], v[232:235], v[16:19]
	v_mfma_f32_16x16x32_bf16 v[4:7], v[170:173], v[240:243], v[4:7]
	v_mfma_f32_16x16x32_bf16 v[0:3], v[194:197], v[240:243], v[0:3]
	s_setprio 0
	s_barrier
	s_add_i32 s6, 0, 0x18000
	s_add_i32 s7, 0, 0x1c000
	v_add_u32_e32 v162, s6, v155
	v_add_u32_e32 v194, s7, v155
	ds_read_b128 v[128:131], v162
	ds_read_b128 v[132:135], v162 offset:1024
	ds_read_b128 v[158:161], v162 offset:2048
	ds_read_b128 v[162:165], v162 offset:3072
	ds_read_b128 v[166:169], v194
	ds_read_b128 v[170:173], v194 offset:1024
	ds_read_b128 v[190:193], v194 offset:2048
	ds_read_b128 v[194:197], v194 offset:3072
	s_add_u32 s4, s18, 0x40000
	s_addc_u32 s5, s19, 0
	s_mov_b32 m0, s64
	v_lshl_add_u64 v[246:247], s[4:5], 0, v[140:141]
	ds_read_b128 v[198:201], v157 offset:32768
	ds_read_b128 v[202:205], v157 offset:33792
	ds_read_b128 v[220:223], v157 offset:34816
	ds_read_b128 v[224:227], v157 offset:35840
	ds_read_b128 v[228:231], v157 offset:36864
	ds_read_b128 v[232:235], v157 offset:37888
	ds_read_b128 v[236:239], v157 offset:38912
	ds_read_b128 v[240:243], v157 offset:39936
	global_load_lds_dwordx4 v[246:247], off
	v_lshl_add_u64 v[246:247], s[4:5], 0, v[138:139]
	s_mov_b32 m0, s65
	s_nop 0
	global_load_lds_dwordx4 v[246:247], off
	s_waitcnt vmcnt(8)
	s_waitcnt lgkmcnt(0)
	s_barrier
	s_setprio 1
	s_waitcnt lgkmcnt(0)
	v_mfma_f32_16x16x32_bf16 v[124:127], v[128:131], v[198:201], v[124:127]
	v_mfma_f32_16x16x32_bf16 v[120:123], v[158:161], v[198:201], v[120:123]
	v_mfma_f32_16x16x32_bf16 v[108:111], v[128:131], v[220:223], v[108:111]
	v_mfma_f32_16x16x32_bf16 v[104:107], v[158:161], v[220:223], v[104:107]
	v_mfma_f32_16x16x32_bf16 v[92:95], v[128:131], v[228:231], v[92:95]
	v_mfma_f32_16x16x32_bf16 v[88:91], v[158:161], v[228:231], v[88:91]
	v_mfma_f32_16x16x32_bf16 v[76:79], v[128:131], v[236:239], v[76:79]
	v_mfma_f32_16x16x32_bf16 v[72:75], v[158:161], v[236:239], v[72:75]
	v_mfma_f32_16x16x32_bf16 v[124:127], v[132:135], v[202:205], v[124:127]
	v_mfma_f32_16x16x32_bf16 v[120:123], v[162:165], v[202:205], v[120:123]
	v_mfma_f32_16x16x32_bf16 v[108:111], v[132:135], v[224:227], v[108:111]
	v_mfma_f32_16x16x32_bf16 v[104:107], v[162:165], v[224:227], v[104:107]
	v_mfma_f32_16x16x32_bf16 v[92:95], v[132:135], v[232:235], v[92:95]
	v_mfma_f32_16x16x32_bf16 v[88:91], v[162:165], v[232:235], v[88:91]
	v_mfma_f32_16x16x32_bf16 v[76:79], v[132:135], v[240:243], v[76:79]
	v_mfma_f32_16x16x32_bf16 v[72:75], v[162:165], v[240:243], v[72:75]
	s_setprio 0
	s_setprio 1
	v_mfma_f32_16x16x32_bf16 v[116:119], v[166:169], v[198:201], v[116:119]
	v_mfma_f32_16x16x32_bf16 v[112:115], v[190:193], v[198:201], v[112:115]
	v_mfma_f32_16x16x32_bf16 v[100:103], v[166:169], v[220:223], v[100:103]
	v_mfma_f32_16x16x32_bf16 v[96:99], v[190:193], v[220:223], v[96:99]
	v_mfma_f32_16x16x32_bf16 v[84:87], v[166:169], v[228:231], v[84:87]
	v_mfma_f32_16x16x32_bf16 v[80:83], v[190:193], v[228:231], v[80:83]
	v_mfma_f32_16x16x32_bf16 v[68:71], v[166:169], v[236:239], v[68:71]
	v_mfma_f32_16x16x32_bf16 v[64:67], v[190:193], v[236:239], v[64:67]
	v_mfma_f32_16x16x32_bf16 v[116:119], v[170:173], v[202:205], v[116:119]
	v_mfma_f32_16x16x32_bf16 v[112:115], v[194:197], v[202:205], v[112:115]
	v_mfma_f32_16x16x32_bf16 v[100:103], v[170:173], v[224:227], v[100:103]
	v_mfma_f32_16x16x32_bf16 v[96:99], v[194:197], v[224:227], v[96:99]
	v_mfma_f32_16x16x32_bf16 v[84:87], v[170:173], v[232:235], v[84:87]
	v_mfma_f32_16x16x32_bf16 v[80:83], v[194:197], v[232:235], v[80:83]
	v_mfma_f32_16x16x32_bf16 v[68:71], v[170:173], v[240:243], v[68:71]
	v_mfma_f32_16x16x32_bf16 v[64:67], v[194:197], v[240:243], v[64:67]
	s_setprio 0
	s_barrier
; #define PG8_STAGE(bufoff, gbase, voff) do { _Pragma("unroll") for (int _i = 0; _i < 2; ++_i) \
;         __builtin_amdgcn_global_load_lds((const unsigned*)((const char*)(gbase) + (voff)[_i]), (PG8_LAS unsigned*)(lds + (bufoff) + ldsw + _i * 8192), 16, 0, 0); } while (0)
; #define PG8_LDA(dst, b, h) do { _Pragma("unroll") for (int m = 0; m < 4; ++m) _Pragma("unroll") for (int k = 0; k < 2; ++k) dst[m][k] = *(const PG8_LAS bf16x8*)(lds + PG8_SA(b, h) + aoff + m * 2048 + k * 1024); } while (0)
; #define PG8_MMA(ai, bj, At, Bt) do { __builtin_amdgcn_s_setprio(1); _Pragma("unroll") for (int m = 0; m < 4; ++m) _Pragma("unroll") for (int n = 0; n < 2; ++n) _Pragma("unroll") for (int k = 0; k < 2; ++k) \
;         acc[ai][bj][m][n] = __builtin_amdgcn_mfma_f32_16x16x32_bf16(Bt[n][k], At[m][k], acc[ai][bj][m][n], 0, 0, 0); __builtin_amdgcn_s_setprio(0); } while (0)
; #define PG8_WAIT_V(n) asm volatile("s_waitcnt vmcnt(" #n ")" ::: "memory")
; #define PG8_WAIT_L(n) asm volatile("s_waitcnt lgkmcnt(" #n ")" ::: "memory")
; #define PG8_BAR __builtin_amdgcn_s_barrier()
; #define PG8_SCHED __builtin_amdgcn_sched_barrier(0)
; template <class Epi, class Sched, bool ALIGN_EPI = false, bool SP2 = false, bool TILED = false>
; __device__ __forceinline__ void gemm_phase(PG8_LAS unsigned char* lds, const Gemm g, const Sched& S, const Epi& E) {
;     ...
;             PG8_LDA(At, 1, 1); PG8_STAGE(PG8_SB(1, 0), b3, voffB); PG8_STAGE(PG8_SB(1, 1), b3 + hstep, voffB); PG8_STAGE(PG8_SA(1, 0), a3, voffA);
;             PG8_WAIT_V(8); PG8_WAIT_L(0); PG8_BAR; PG8_MMA(1, 0, At, B0); PG8_MMA(1, 1, At, B1); PG8_BAR; PG8_SCHED;
	s_add_i32 s4, s6, s34
	v_lshl_add_u64 v[150:151], v[150:151], 0, s[26:27]
	s_mov_b32 m0, s4
	ds_read_b128 v[198:201], v157 offset:49152
	ds_read_b128 v[202:205], v157 offset:50176
	ds_read_b128 v[220:223], v157 offset:51200
	ds_read_b128 v[224:227], v157 offset:52224
	ds_read_b128 v[228:231], v157 offset:53248
	ds_read_b128 v[232:235], v157 offset:54272
	ds_read_b128 v[236:239], v157 offset:55296
	ds_read_b128 v[240:243], v157 offset:56320
	global_load_lds_dwordx4 v[150:151], off
	s_add_i32 m0, s4, 0x2000
	s_add_u32 s0, s0, 0x40080
	v_lshl_add_u64 v[150:151], v[174:175], 0, s[26:27]
	s_addc_u32 s1, s1, 0
	s_add_i32 s4, s7, s34
	global_load_lds_dwordx4 v[150:151], off
	v_lshl_add_u64 v[150:151], s[0:1], 0, v[176:177]
	s_mov_b32 m0, s4
	s_nop 0
	global_load_lds_dwordx4 v[150:151], off
	v_lshl_add_u64 v[150:151], s[0:1], 0, v[136:137]
	s_add_i32 m0, s4, 0x2000
	s_nop 0
	global_load_lds_dwordx4 v[150:151], off
	v_lshl_add_u64 v[150:151], v[206:207], 0, s[26:27]
	s_mov_b32 m0, s72
	s_nop 0
	global_load_lds_dwordx4 v[150:151], off
	v_lshl_add_u64 v[150:151], v[244:245], 0, s[26:27]
	s_mov_b32 m0, s73
	s_nop 0
	global_load_lds_dwordx4 v[150:151], off
	s_waitcnt vmcnt(8)
	s_waitcnt lgkmcnt(0)
	s_barrier
	s_setprio 1
	s_waitcnt lgkmcnt(0)
	v_mfma_f32_16x16x32_bf16 v[60:63], v[128:131], v[198:201], v[60:63]
	v_mfma_f32_16x16x32_bf16 v[56:59], v[158:161], v[198:201], v[56:59]
	v_mfma_f32_16x16x32_bf16 v[44:47], v[128:131], v[220:223], v[44:47]
	v_mfma_f32_16x16x32_bf16 v[40:43], v[158:161], v[220:223], v[40:43]
	v_mfma_f32_16x16x32_bf16 v[28:31], v[128:131], v[228:231], v[28:31]
	v_mfma_f32_16x16x32_bf16 v[24:27], v[158:161], v[228:231], v[24:27]
	v_mfma_f32_16x16x32_bf16 v[12:15], v[128:131], v[236:239], v[12:15]
	v_mfma_f32_16x16x32_bf16 v[8:11], v[158:161], v[236:239], v[8:11]
	v_mfma_f32_16x16x32_bf16 v[60:63], v[132:135], v[202:205], v[60:63]
	v_mfma_f32_16x16x32_bf16 v[56:59], v[162:165], v[202:205], v[56:59]
	v_mfma_f32_16x16x32_bf16 v[44:47], v[132:135], v[224:227], v[44:47]
	v_mfma_f32_16x16x32_bf16 v[40:43], v[162:165], v[224:227], v[40:43]
	v_mfma_f32_16x16x32_bf16 v[28:31], v[132:135], v[232:235], v[28:31]
	v_mfma_f32_16x16x32_bf16 v[24:27], v[162:165], v[232:235], v[24:27]
	v_mfma_f32_16x16x32_bf16 v[12:15], v[132:135], v[240:243], v[12:15]
	v_mfma_f32_16x16x32_bf16 v[8:11], v[162:165], v[240:243], v[8:11]
	s_setprio 0
	s_setprio 1
	v_mfma_f32_16x16x32_bf16 v[52:55], v[166:169], v[198:201], v[52:55]
	v_mfma_f32_16x16x32_bf16 v[48:51], v[190:193], v[198:201], v[48:51]
	v_mfma_f32_16x16x32_bf16 v[36:39], v[166:169], v[220:223], v[36:39]
	v_mfma_f32_16x16x32_bf16 v[32:35], v[190:193], v[220:223], v[32:35]
	v_mfma_f32_16x16x32_bf16 v[20:23], v[166:169], v[228:231], v[20:23]
	v_mfma_f32_16x16x32_bf16 v[16:19], v[190:193], v[228:231], v[16:19]
	v_mfma_f32_16x16x32_bf16 v[4:7], v[166:169], v[236:239], v[4:7]
	v_mfma_f32_16x16x32_bf16 v[0:3], v[190:193], v[236:239], v[0:3]
	v_mfma_f32_16x16x32_bf16 v[52:55], v[170:173], v[202:205], v[52:55]
	v_mfma_f32_16x16x32_bf16 v[48:51], v[194:197], v[202:205], v[48:51]
	v_mfma_f32_16x16x32_bf16 v[36:39], v[170:173], v[224:227], v[36:39]
	v_mfma_f32_16x16x32_bf16 v[32:35], v[194:197], v[224:227], v[32:35]
	v_mfma_f32_16x16x32_bf16 v[20:23], v[170:173], v[232:235], v[20:23]
	v_mfma_f32_16x16x32_bf16 v[16:19], v[194:197], v[232:235], v[16:19]
	v_mfma_f32_16x16x32_bf16 v[4:7], v[170:173], v[240:243], v[4:7]
	v_mfma_f32_16x16x32_bf16 v[0:3], v[194:197], v[240:243], v[0:3]
	s_setprio 0
	s_barrier
	s_add_i32 s40, s40, 2
	s_add_u32 s16, s16, 0x100
	s_addc_u32 s17, s17, 0
	s_cmp_gt_u32 s40, 13
	s_cbranch_scc1 .LBB0_647

; #define PG8_STAGE(bufoff, gbase, voff) do { _Pragma("unroll") for (int _i = 0; _i < 2; ++_i) \
;         __builtin_amdgcn_global_load_lds((const unsigned*)((const char*)(gbase) + (voff)[_i]), (PG8_LAS unsigned*)(lds + (bufoff) + ldsw + _i * 8192), 16, 0, 0); } while (0)
; #define PG8_WAIT_V(n) asm volatile("s_waitcnt vmcnt(" #n ")" ::: "memory")
; #define PG8_BAR __builtin_amdgcn_s_barrier()
; template <class Epi, class Sched, bool ALIGN_EPI = false, bool SP2 = false, bool TILED = false>
; __device__ __forceinline__ void gemm_phase(PG8_LAS unsigned char* lds, const Gemm g, const Sched& S, const Epi& E) {
;     ...
;     for (int i = 0; i < 2; ++i) { int R, C; stage_rc(tid * 16 + i * 8192, R, C); const int Rb = Epi::PERM ? ((R & ~31) + perm32(R & 31)) : R;
;         const int rs = TILED ? BK : K; voffA[i] = (unsigned)(R * rs + C) * 2u; voffB[i] = (unsigned)(Rb * rs + C) * 2u; }
;     const size_t kstep = TILED ? (size_t)(BM * BK * 2) : (size_t)(BK * 2);
;     const size_t hstep = TILED ? (size_t)(HALF * BK * 2) : (size_t)HALF * K * 2;
;     const size_t tstep = TILED ? (size_t)(K / BK) * (BM * BK * 2) : 2 * hstep;
;     const unsigned ldsw = (unsigned)wid * 1024u;
;     const int aoff = lds_byte(wr * 64 + fr, fq * 8), boff = lds_byte(wc * 32 + fr, fq * 8);
;     ...
;     Unit cur, nxt; int ui = 0;
;     if (!S.next(0, cur)) return;
;     f32x4 acc[2][2][4][2];
; #pragma unroll
;     for (int a = 0; a < 2; ++a)
; #pragma unroll
;         for (int b = 0; b < 2; ++b)
; #pragma unroll
;             for (int m = 0; m < 4; ++m)
; #pragma unroll
;                 for (int n = 0; n < 2; ++n) acc[a][b][m][n] = (f32x4){0.f, 0.f, 0.f, 0.f};
;     bf16x8 At[4][2], B0[2][2], B1[2][2];
;     const char* cA = (const char*)g.A + (size_t)cur.pm * tstep; const char* cB = (const char*)g.Bt + (size_t)cur.pn * tstep;
;     S.a_ready(cur);
;     if constexpr (SP2) {
;         PG8_STAGE(PG8_SB(0, 0), cB, voffB); PG8_STAGE(PG8_SB(0, 1), cB + hstep, voffB); PG8_STAGE(PG8_SA(0, 0), cA, voffA); PG8_STAGE(PG8_SA(0, 1), cA + hstep, voffA);
;         if (wr == 1) PG8_BAR;
;         PG8_WAIT_V(2); PG8_BAR;
;         PG8_STAGE(PG8_SB(1, 0), cB + kstep, voffB); PG8_STAGE(PG8_SA(1, 0), cA + kstep, voffA); PG8_STAGE(PG8_SB(1, 1), cB + hstep + kstep, voffB);
;         PG8_WAIT_V(6); PG8_BAR;
.LBB0_709:
	v_bfe_u32 v16, v6, 4, 2
	v_readlane_b32 s18, v249, 15
	v_and_b32_e32 v7, 15, v6
	v_lshlrev_b32_e32 v17, 4, v16
	v_lshlrev_b32_e32 v6, 2, v6
	s_lshl_b32 s1, s1, 5
	v_readlane_b32 s19, v249, 16
	v_lshl_or_b32 v219, s9, 6, v7
	v_lshl_or_b32 v7, v7, 6, v17
	s_lshl_b32 s9, s9, 13
	v_and_b32_e32 v6, 32, v6
	s_and_b32 s1, s1, 0x60
	v_lshl_add_u64 v[8:9], s[18:19], 0, v[176:177]
	v_mov_b32_e32 v191, v177
	v_readlane_b32 s20, v249, 11
	v_bitop3_b32 v17, v7, s9, v6 bitop3:0xde
	s_lshl_b32 s9, s1, 7
	v_lshl_add_u64 v[10:11], s[18:19], 0, v[190:191]
	v_readlane_b32 s21, v249, 12
	v_bitop3_b32 v220, v7, s9, v6 bitop3:0xde
	s_add_i32 m0, s5, 0x18000
	v_lshl_add_u64 v[6:7], v[8:9], 0, s[26:27]
	s_waitcnt vmcnt(0)
	v_lshl_add_u64 v[12:13], s[20:21], 0, v[176:177]
	s_waitcnt vmcnt(2)
	s_barrier
	global_load_lds_dwordx4 v[6:7], off
	v_lshl_add_u64 v[6:7], v[10:11], 0, s[26:27]
	s_add_i32 m0, s5, 0x1a000
	s_add_i32 s9, s5, 0x8000
	v_lshl_add_u64 v[14:15], s[20:21], 0, v[190:191]
	global_load_lds_dwordx4 v[6:7], off
	v_lshl_add_u64 v[6:7], v[12:13], 0, s[26:27]
	s_mov_b32 m0, s9
	s_add_i32 s34, s5, 0xa000
	v_readlane_b32 s10, v249, 17
	global_load_lds_dwordx4 v[6:7], off
	v_lshl_add_u64 v[6:7], v[14:15], 0, s[26:27]
	s_mov_b32 m0, s34
	v_readlane_b32 s11, v249, 18
	global_load_lds_dwordx4 v[6:7], off
	s_add_i32 m0, s5, 0x1c000
	v_lshl_add_u64 v[6:7], s[10:11], 0, v[176:177]
	global_load_lds_dwordx4 v[6:7], off
	v_lshl_add_u64 v[6:7], s[10:11], 0, v[190:191]
	s_add_i32 m0, s5, 0x1e000
	s_cmpk_lt_u32 s0, 0x100
	global_load_lds_dwordx4 v[6:7], off
	v_lshlrev_b32_e32 v6, 14, v3
	v_and_b32_e32 v6, 0xffff8000, v6
	v_lshl_add_u32 v4, v4, 11, v6
	v_and_b32_e32 v3, 1, v3
	v_lshl_or_b32 v3, v3, 6, v4
	v_lshl_add_u32 v192, v5, 1, v3
	v_lshlrev_b32_e32 v3, 14, v0
	v_and_b32_e32 v3, 0xffff8000, v3
	s_waitcnt vmcnt(0)
	v_lshl_or_b32 v221, v16, 2, s1
	v_lshl_add_u32 v1, v1, 11, v3
	v_and_b32_e32 v0, 1, v0
	v_readlane_b32 s0, v249, 19
	v_lshl_or_b32 v0, v0, 6, v1
	v_readlane_b32 s1, v249, 20
	s_cselect_b64 s[16:17], -1, 0
	s_mov_b32 s40, 0
	v_cmp_eq_u32_e64 s[42:43], 0, v16
	v_mov_b32_e32 v193, v177
	v_lshl_add_u32 v194, v2, 1, v0
	v_mov_b32_e32 v195, v177
	v_add_u32_e32 v222, 0, v17
	v_readlane_b32 s10, v250, 31
	s_mov_b32 s11, s0
	s_mov_b64 s[0:1], s[18:19]
	s_mov_b64 s[18:19], s[20:21]
	s_barrier
	s_branch .LBB0_712

; #define PG8_STAGE(bufoff, gbase, voff) do { _Pragma("unroll") for (int _i = 0; _i < 2; ++_i) \
;         __builtin_amdgcn_global_load_lds((const unsigned*)((const char*)(gbase) + (voff)[_i]), (PG8_LAS unsigned*)(lds + (bufoff) + ldsw + _i * 8192), 16, 0, 0); } while (0)
; #define PG8_LDA(dst, b, h) do { _Pragma("unroll") for (int m = 0; m < 4; ++m) _Pragma("unroll") for (int k = 0; k < 2; ++k) dst[m][k] = *(const PG8_LAS bf16x8*)(lds + PG8_SA(b, h) + aoff + m * 2048 + k * 1024); } while (0)
; #define PG8_LDB(dst, b, h) do { _Pragma("unroll") for (int n = 0; n < 2; ++n) _Pragma("unroll") for (int k = 0; k < 2; ++k) dst[n][k] = *(const PG8_LAS bf16x8*)(lds + PG8_SB(b, h) + boff + n * 2048 + k * 1024); } while (0)
; #define PG8_MMA(ai, bj, At, Bt) do { __builtin_amdgcn_s_setprio(1); _Pragma("unroll") for (int m = 0; m < 4; ++m) _Pragma("unroll") for (int n = 0; n < 2; ++n) _Pragma("unroll") for (int k = 0; k < 2; ++k) \
;         acc[ai][bj][m][n] = __builtin_amdgcn_mfma_f32_16x16x32_bf16(Bt[n][k], At[m][k], acc[ai][bj][m][n], 0, 0, 0); __builtin_amdgcn_s_setprio(0); } while (0)
; #define PG8_WAIT_V(n) asm volatile("s_waitcnt vmcnt(" #n ")" ::: "memory")
; #define PG8_WAIT_L(n) asm volatile("s_waitcnt lgkmcnt(" #n ")" ::: "memory")
; #define PG8_BAR __builtin_amdgcn_s_barrier()
; #define PG8_SCHED __builtin_amdgcn_sched_barrier(0)
; template <class Epi, class Sched, bool ALIGN_EPI = false, bool SP2 = false, bool TILED = false>
; __device__ __forceinline__ void gemm_phase(PG8_LAS unsigned char* lds, const Gemm g, const Sched& S, const Epi& E) {
;     ...
;             PG8_LDB(B0, 0, 0); PG8_LDB(B1, 0, 1); PG8_SCHED; PG8_LDA(At, 0, 0); PG8_STAGE(PG8_SA(1, 1), a1 + hstep, voffA);
;             PG8_WAIT_V(8); PG8_WAIT_L(0); PG8_BAR; PG8_MMA(0, 0, At, B0); PG8_MMA(0, 1, At, B1); PG8_BAR; PG8_SCHED;
;             PG8_LDA(At, 0, 1); PG8_STAGE(PG8_SB(0, 0), b2, voffB); PG8_STAGE(PG8_SB(0, 1), b2 + hstep, voffB); PG8_STAGE(PG8_SA(0, 0), a2, voffA);
.LBB0_719:
	s_add_u32 s0, s72, 0xfffc0080
	s_addc_u32 s1, s73, -1
	s_add_i32 s12, 0, 0x10000
	s_cmp_eq_u32 s55, 12
	s_cselect_b32 s19, s38, s1
	s_cselect_b32 s18, s39, s0
	s_cselect_b32 s1, s41, s54
	s_cselect_b32 s0, s51, s53
	s_add_i32 s35, 0, 0x14000
	v_add_u32_e32 v140, s12, v220
	v_add_u32_e32 v156, s35, v220
	ds_read_b128 v[128:131], v140
	ds_read_b128 v[132:135], v140 offset:1024
	ds_read_b128 v[136:139], v140 offset:2048
	ds_read_b128 v[140:143], v140 offset:3072
	ds_read_b128 v[144:147], v156
	ds_read_b128 v[148:151], v156 offset:1024
	ds_read_b128 v[152:155], v156 offset:2048
	ds_read_b128 v[156:159], v156 offset:3072
	v_lshl_add_u64 v[228:229], s[72:73], 0, v[192:193]
	s_add_i32 m0, s5, 0xc000
	ds_read_b128 v[160:163], v222
	ds_read_b128 v[164:167], v222 offset:1024
	ds_read_b128 v[168:171], v222 offset:2048
	ds_read_b128 v[172:175], v222 offset:3072
	ds_read_b128 v[196:199], v222 offset:4096
	ds_read_b128 v[200:203], v222 offset:5120
	ds_read_b128 v[204:207], v222 offset:6144
	ds_read_b128 v[224:227], v222 offset:7168
	global_load_lds_dwordx4 v[228:229], off
	v_lshl_add_u64 v[228:229], s[72:73], 0, v[194:195]
	s_add_i32 m0, s5, 0xe000
	s_nop 0
	global_load_lds_dwordx4 v[228:229], off
	s_cmp_eq_u32 s55, -2
	s_cbranch_scc1 .Lmyw_4
	s_waitcnt vmcnt(8)
.Lmyw_4:
	s_waitcnt lgkmcnt(0)
	s_barrier
	s_setprio 1
	s_waitcnt lgkmcnt(0)
	v_mfma_f32_16x16x32_bf16 v[124:127], v[128:131], v[160:163], v[124:127]
	v_mfma_f32_16x16x32_bf16 v[120:123], v[136:139], v[160:163], v[120:123]
	v_mfma_f32_16x16x32_bf16 v[108:111], v[128:131], v[168:171], v[108:111]
	v_mfma_f32_16x16x32_bf16 v[104:107], v[136:139], v[168:171], v[104:107]
	v_mfma_f32_16x16x32_bf16 v[92:95], v[128:131], v[196:199], v[92:95]
	v_mfma_f32_16x16x32_bf16 v[88:91], v[136:139], v[196:199], v[88:91]
	v_mfma_f32_16x16x32_bf16 v[76:79], v[128:131], v[204:207], v[76:79]
	v_mfma_f32_16x16x32_bf16 v[72:75], v[136:139], v[204:207], v[72:75]
	v_mfma_f32_16x16x32_bf16 v[124:127], v[132:135], v[164:167], v[124:127]
	v_mfma_f32_16x16x32_bf16 v[120:123], v[140:143], v[164:167], v[120:123]
	v_mfma_f32_16x16x32_bf16 v[108:111], v[132:135], v[172:175], v[108:111]
	v_mfma_f32_16x16x32_bf16 v[104:107], v[140:143], v[172:175], v[104:107]
	v_mfma_f32_16x16x32_bf16 v[92:95], v[132:135], v[200:203], v[92:95]
	v_mfma_f32_16x16x32_bf16 v[88:91], v[140:143], v[200:203], v[88:91]
	v_mfma_f32_16x16x32_bf16 v[76:79], v[132:135], v[224:227], v[76:79]
	v_mfma_f32_16x16x32_bf16 v[72:75], v[140:143], v[224:227], v[72:75]
	s_setprio 0
	s_setprio 1
	v_mfma_f32_16x16x32_bf16 v[116:119], v[144:147], v[160:163], v[116:119]
	v_mfma_f32_16x16x32_bf16 v[112:115], v[152:155], v[160:163], v[112:115]
	v_mfma_f32_16x16x32_bf16 v[100:103], v[144:147], v[168:171], v[100:103]
	v_mfma_f32_16x16x32_bf16 v[96:99], v[152:155], v[168:171], v[96:99]
	v_mfma_f32_16x16x32_bf16 v[84:87], v[144:147], v[196:199], v[84:87]
	v_mfma_f32_16x16x32_bf16 v[80:83], v[152:155], v[196:199], v[80:83]
	v_mfma_f32_16x16x32_bf16 v[68:71], v[144:147], v[204:207], v[68:71]
	v_mfma_f32_16x16x32_bf16 v[64:67], v[152:155], v[204:207], v[64:67]
	v_mfma_f32_16x16x32_bf16 v[116:119], v[148:151], v[164:167], v[116:119]
	v_mfma_f32_16x16x32_bf16 v[112:115], v[156:159], v[164:167], v[112:115]
	v_mfma_f32_16x16x32_bf16 v[100:103], v[148:151], v[172:175], v[100:103]
	v_mfma_f32_16x16x32_bf16 v[96:99], v[156:159], v[172:175], v[96:99]
	v_mfma_f32_16x16x32_bf16 v[84:87], v[148:151], v[200:203], v[84:87]
	v_mfma_f32_16x16x32_bf16 v[80:83], v[156:159], v[200:203], v[80:83]
	v_mfma_f32_16x16x32_bf16 v[68:71], v[148:151], v[224:227], v[68:71]
	v_mfma_f32_16x16x32_bf16 v[64:67], v[156:159], v[224:227], v[64:67]
	s_setprio 0
	s_barrier
	s_add_i32 s12, s12, s4
	v_lshl_add_u64 v[228:229], s[0:1], 0, v[176:177]
	s_mov_b32 m0, s12
	ds_read_b128 v[160:163], v222 offset:16384
	ds_read_b128 v[164:167], v222 offset:17408
	ds_read_b128 v[168:171], v222 offset:18432
	ds_read_b128 v[172:175], v222 offset:19456
	ds_read_b128 v[196:199], v222 offset:20480
	ds_read_b128 v[200:203], v222 offset:21504
	ds_read_b128 v[204:207], v222 offset:22528
	ds_read_b128 v[224:227], v222 offset:23552
	global_load_lds_dwordx4 v[228:229], off
	s_add_i32 m0, s12, 0x2000
	s_add_u32 s20, s0, 0x40000
	v_lshl_add_u64 v[230:231], s[0:1], 0, v[190:191]
	s_addc_u32 s21, s1, 0
	s_add_i32 s12, s35, s4
	global_load_lds_dwordx4 v[230:231], off
	v_lshl_add_u64 v[232:233], s[20:21], 0, v[176:177]
	s_mov_b32 m0, s12
	v_lshl_add_u64 v[234:235], s[18:19], 0, v[190:191]
	global_load_lds_dwordx4 v[232:233], off
	v_lshl_add_u64 v[232:233], s[20:21], 0, v[190:191]
	s_add_i32 m0, s12, 0x2000
	s_nop 0
	global_load_lds_dwordx4 v[232:233], off
	v_lshl_add_u64 v[232:233], s[18:19], 0, v[176:177]
	s_mov_b32 m0, s5
	s_nop 0
	global_load_lds_dwordx4 v[232:233], off
	s_mov_b32 m0, s6
	s_nop 0
	global_load_lds_dwordx4 v[234:235], off
	s_cmp_eq_u32 s55, -2
	s_cbranch_scc1 .Lmyw_5
	s_waitcnt vmcnt(8)
; #define PG8_STAGE(bufoff, gbase, voff) do { _Pragma("unroll") for (int _i = 0; _i < 2; ++_i) \
;         __builtin_amdgcn_global_load_lds((const unsigned*)((const char*)(gbase) + (voff)[_i]), (PG8_LAS unsigned*)(lds + (bufoff) + ldsw + _i * 8192), 16, 0, 0); } while (0)
; #define PG8_LDA(dst, b, h) do { _Pragma("unroll") for (int m = 0; m < 4; ++m) _Pragma("unroll") for (int k = 0; k < 2; ++k) dst[m][k] = *(const PG8_LAS bf16x8*)(lds + PG8_SA(b, h) + aoff + m * 2048 + k * 1024); } while (0)
; #define PG8_LDB(dst, b, h) do { _Pragma("unroll") for (int n = 0; n < 2; ++n) _Pragma("unroll") for (int k = 0; k < 2; ++k) dst[n][k] = *(const PG8_LAS bf16x8*)(lds + PG8_SB(b, h) + boff + n * 2048 + k * 1024); } while (0)
; #define PG8_MMA(ai, bj, At, Bt) do { __builtin_amdgcn_s_setprio(1); _Pragma("unroll") for (int m = 0; m < 4; ++m) _Pragma("unroll") for (int n = 0; n < 2; ++n) _Pragma("unroll") for (int k = 0; k < 2; ++k) \
;         acc[ai][bj][m][n] = __builtin_amdgcn_mfma_f32_16x16x32_bf16(Bt[n][k], At[m][k], acc[ai][bj][m][n], 0, 0, 0); __builtin_amdgcn_s_setprio(0); } while (0)
; #define PG8_WAIT_V(n) asm volatile("s_waitcnt vmcnt(" #n ")" ::: "memory")
; #define PG8_WAIT_L(n) asm volatile("s_waitcnt lgkmcnt(" #n ")" ::: "memory")
; #define PG8_BAR __builtin_amdgcn_s_barrier()
; #define PG8_SCHED __builtin_amdgcn_sched_barrier(0)
; template <class Epi, class Sched, bool ALIGN_EPI = false, bool SP2 = false, bool TILED = false>
; __device__ __forceinline__ void gemm_phase(PG8_LAS unsigned char* lds, const Gemm g, const Sched& S, const Epi& E) {
;     ...
;             PG8_WAIT_V(8); PG8_WAIT_L(0); PG8_BAR; PG8_MMA(1, 0, At, B0); PG8_MMA(1, 1, At, B1); PG8_BAR; PG8_SCHED;
;             PG8_LDB(B0, 1, 0); PG8_LDB(B1, 1, 1); PG8_SCHED; PG8_LDA(At, 1, 0); PG8_STAGE(PG8_SA(0, 1), a2 + hstep, voffA);
;             PG8_WAIT_V(8); PG8_WAIT_L(0); PG8_BAR; PG8_MMA(0, 0, At, B0); PG8_MMA(0, 1, At, B1); PG8_BAR; PG8_SCHED;
.Lmyw_5:
	s_waitcnt lgkmcnt(0)
	s_barrier
	s_setprio 1
	s_waitcnt lgkmcnt(0)
	v_mfma_f32_16x16x32_bf16 v[60:63], v[128:131], v[160:163], v[60:63]
	v_mfma_f32_16x16x32_bf16 v[56:59], v[136:139], v[160:163], v[56:59]
	v_mfma_f32_16x16x32_bf16 v[44:47], v[128:131], v[168:171], v[44:47]
	v_mfma_f32_16x16x32_bf16 v[40:43], v[136:139], v[168:171], v[40:43]
	v_mfma_f32_16x16x32_bf16 v[28:31], v[128:131], v[196:199], v[28:31]
	v_mfma_f32_16x16x32_bf16 v[24:27], v[136:139], v[196:199], v[24:27]
	v_mfma_f32_16x16x32_bf16 v[12:15], v[128:131], v[204:207], v[12:15]
	v_mfma_f32_16x16x32_bf16 v[8:11], v[136:139], v[204:207], v[8:11]
	v_mfma_f32_16x16x32_bf16 v[60:63], v[132:135], v[164:167], v[60:63]
	v_mfma_f32_16x16x32_bf16 v[56:59], v[140:143], v[164:167], v[56:59]
	v_mfma_f32_16x16x32_bf16 v[44:47], v[132:135], v[172:175], v[44:47]
	v_mfma_f32_16x16x32_bf16 v[40:43], v[140:143], v[172:175], v[40:43]
	v_mfma_f32_16x16x32_bf16 v[28:31], v[132:135], v[200:203], v[28:31]
	v_mfma_f32_16x16x32_bf16 v[24:27], v[140:143], v[200:203], v[24:27]
	v_mfma_f32_16x16x32_bf16 v[12:15], v[132:135], v[224:227], v[12:15]
	v_mfma_f32_16x16x32_bf16 v[8:11], v[140:143], v[224:227], v[8:11]
	s_setprio 0
	s_setprio 1
	v_mfma_f32_16x16x32_bf16 v[52:55], v[144:147], v[160:163], v[52:55]
	v_mfma_f32_16x16x32_bf16 v[48:51], v[152:155], v[160:163], v[48:51]
	v_mfma_f32_16x16x32_bf16 v[36:39], v[144:147], v[168:171], v[36:39]
	v_mfma_f32_16x16x32_bf16 v[32:35], v[152:155], v[168:171], v[32:35]
	v_mfma_f32_16x16x32_bf16 v[20:23], v[144:147], v[196:199], v[20:23]
	v_mfma_f32_16x16x32_bf16 v[16:19], v[152:155], v[196:199], v[16:19]
	v_mfma_f32_16x16x32_bf16 v[4:7], v[144:147], v[204:207], v[4:7]
	v_mfma_f32_16x16x32_bf16 v[0:3], v[152:155], v[204:207], v[0:3]
	v_mfma_f32_16x16x32_bf16 v[52:55], v[148:151], v[164:167], v[52:55]
	v_mfma_f32_16x16x32_bf16 v[48:51], v[156:159], v[164:167], v[48:51]
	v_mfma_f32_16x16x32_bf16 v[36:39], v[148:151], v[172:175], v[36:39]
	v_mfma_f32_16x16x32_bf16 v[32:35], v[156:159], v[172:175], v[32:35]
	v_mfma_f32_16x16x32_bf16 v[20:23], v[148:151], v[200:203], v[20:23]
	v_mfma_f32_16x16x32_bf16 v[16:19], v[156:159], v[200:203], v[16:19]
	v_mfma_f32_16x16x32_bf16 v[4:7], v[148:151], v[224:227], v[4:7]
	v_mfma_f32_16x16x32_bf16 v[0:3], v[156:159], v[224:227], v[0:3]
	s_setprio 0
	s_barrier
	s_add_i32 s12, 0, 0x18000
	s_add_i32 s20, 0, 0x1c000
	v_add_u32_e32 v140, s12, v220
	v_add_u32_e32 v156, s20, v220
	ds_read_b128 v[128:131], v140
	ds_read_b128 v[132:135], v140 offset:1024
	ds_read_b128 v[136:139], v140 offset:2048
	ds_read_b128 v[140:143], v140 offset:3072
	ds_read_b128 v[144:147], v156
	ds_read_b128 v[148:151], v156 offset:1024
	ds_read_b128 v[152:155], v156 offset:2048
	ds_read_b128 v[156:159], v156 offset:3072
	s_add_u32 s18, s18, 0x40000
	s_addc_u32 s19, s19, 0
	s_mov_b32 m0, s7
	v_lshl_add_u64 v[236:237], s[18:19], 0, v[176:177]
	ds_read_b128 v[160:163], v222 offset:32768
	ds_read_b128 v[164:167], v222 offset:33792
	ds_read_b128 v[168:171], v222 offset:34816
	ds_read_b128 v[172:175], v222 offset:35840
	ds_read_b128 v[196:199], v222 offset:36864
	ds_read_b128 v[200:203], v222 offset:37888
	ds_read_b128 v[204:207], v222 offset:38912
	ds_read_b128 v[224:227], v222 offset:39936
	global_load_lds_dwordx4 v[236:237], off
	v_lshl_add_u64 v[236:237], s[18:19], 0, v[190:191]
	s_mov_b32 m0, s8
	s_nop 0
	global_load_lds_dwordx4 v[236:237], off
	s_waitcnt vmcnt(8)
	s_waitcnt lgkmcnt(0)
	s_barrier
	s_setprio 1
	s_waitcnt lgkmcnt(0)
	v_mfma_f32_16x16x32_bf16 v[124:127], v[128:131], v[160:163], v[124:127]
	v_mfma_f32_16x16x32_bf16 v[120:123], v[136:139], v[160:163], v[120:123]
	v_mfma_f32_16x16x32_bf16 v[108:111], v[128:131], v[168:171], v[108:111]
	v_mfma_f32_16x16x32_bf16 v[104:107], v[136:139], v[168:171], v[104:107]
	v_mfma_f32_16x16x32_bf16 v[92:95], v[128:131], v[196:199], v[92:95]
	v_mfma_f32_16x16x32_bf16 v[88:91], v[136:139], v[196:199], v[88:91]
	v_mfma_f32_16x16x32_bf16 v[76:79], v[128:131], v[204:207], v[76:79]
	v_mfma_f32_16x16x32_bf16 v[72:75], v[136:139], v[204:207], v[72:75]
	v_mfma_f32_16x16x32_bf16 v[124:127], v[132:135], v[164:167], v[124:127]
	v_mfma_f32_16x16x32_bf16 v[120:123], v[140:143], v[164:167], v[120:123]
	v_mfma_f32_16x16x32_bf16 v[108:111], v[132:135], v[172:175], v[108:111]
	v_mfma_f32_16x16x32_bf16 v[104:107], v[140:143], v[172:175], v[104:107]
	v_mfma_f32_16x16x32_bf16 v[92:95], v[132:135], v[200:203], v[92:95]
	v_mfma_f32_16x16x32_bf16 v[88:91], v[140:143], v[200:203], v[88:91]
	v_mfma_f32_16x16x32_bf16 v[76:79], v[132:135], v[224:227], v[76:79]
	v_mfma_f32_16x16x32_bf16 v[72:75], v[140:143], v[224:227], v[72:75]
	s_setprio 0
	s_setprio 1
	v_mfma_f32_16x16x32_bf16 v[116:119], v[144:147], v[160:163], v[116:119]
	v_mfma_f32_16x16x32_bf16 v[112:115], v[152:155], v[160:163], v[112:115]
	v_mfma_f32_16x16x32_bf16 v[100:103], v[144:147], v[168:171], v[100:103]
	v_mfma_f32_16x16x32_bf16 v[96:99], v[152:155], v[168:171], v[96:99]
	v_mfma_f32_16x16x32_bf16 v[84:87], v[144:147], v[196:199], v[84:87]
	v_mfma_f32_16x16x32_bf16 v[80:83], v[152:155], v[196:199], v[80:83]
	v_mfma_f32_16x16x32_bf16 v[68:71], v[144:147], v[204:207], v[68:71]
	v_mfma_f32_16x16x32_bf16 v[64:67], v[152:155], v[204:207], v[64:67]
	v_mfma_f32_16x16x32_bf16 v[116:119], v[148:151], v[164:167], v[116:119]
	v_mfma_f32_16x16x32_bf16 v[112:115], v[156:159], v[164:167], v[112:115]
	v_mfma_f32_16x16x32_bf16 v[100:103], v[148:151], v[172:175], v[100:103]
	v_mfma_f32_16x16x32_bf16 v[96:99], v[156:159], v[172:175], v[96:99]
	v_mfma_f32_16x16x32_bf16 v[84:87], v[148:151], v[200:203], v[84:87]
	v_mfma_f32_16x16x32_bf16 v[80:83], v[156:159], v[200:203], v[80:83]
	v_mfma_f32_16x16x32_bf16 v[68:71], v[148:151], v[224:227], v[68:71]
	v_mfma_f32_16x16x32_bf16 v[64:67], v[156:159], v[224:227], v[64:67]
	s_setprio 0
	s_barrier
; #define PG8_STAGE(bufoff, gbase, voff) do { _Pragma("unroll") for (int _i = 0; _i < 2; ++_i) \
;         __builtin_amdgcn_global_load_lds((const unsigned*)((const char*)(gbase) + (voff)[_i]), (PG8_LAS unsigned*)(lds + (bufoff) + ldsw + _i * 8192), 16, 0, 0); } while (0)
; #define PG8_LDA(dst, b, h) do { _Pragma("unroll") for (int m = 0; m < 4; ++m) _Pragma("unroll") for (int k = 0; k < 2; ++k) dst[m][k] = *(const PG8_LAS bf16x8*)(lds + PG8_SA(b, h) + aoff + m * 2048 + k * 1024); } while (0)
; #define PG8_MMA(ai, bj, At, Bt) do { __builtin_amdgcn_s_setprio(1); _Pragma("unroll") for (int m = 0; m < 4; ++m) _Pragma("unroll") for (int n = 0; n < 2; ++n) _Pragma("unroll") for (int k = 0; k < 2; ++k) \
;         acc[ai][bj][m][n] = __builtin_amdgcn_mfma_f32_16x16x32_bf16(Bt[n][k], At[m][k], acc[ai][bj][m][n], 0, 0, 0); __builtin_amdgcn_s_setprio(0); } while (0)
; #define PG8_WAIT_V(n) asm volatile("s_waitcnt vmcnt(" #n ")" ::: "memory")
; #define PG8_WAIT_L(n) asm volatile("s_waitcnt lgkmcnt(" #n ")" ::: "memory")
; #define PG8_BAR __builtin_amdgcn_s_barrier()
; #define PG8_SCHED __builtin_amdgcn_sched_barrier(0)
; template <class Epi, class Sched, bool ALIGN_EPI = false, bool SP2 = false, bool TILED = false>
; __device__ __forceinline__ void gemm_phase(PG8_LAS unsigned char* lds, const Gemm g, const Sched& S, const Epi& E) {
;     ...
;             PG8_LDA(At, 1, 1); PG8_STAGE(PG8_SB(1, 0), b3, voffB); PG8_STAGE(PG8_SB(1, 1), b3 + hstep, voffB); PG8_STAGE(PG8_SA(1, 0), a3, voffA);
;             PG8_WAIT_V(8); PG8_WAIT_L(0); PG8_BAR; PG8_MMA(1, 0, At, B0); PG8_MMA(1, 1, At, B1); PG8_BAR; PG8_SCHED;
	s_add_i32 s12, s12, s4
	v_lshl_add_u64 v[228:229], v[228:229], 0, s[26:27]
	s_mov_b32 m0, s12
	ds_read_b128 v[160:163], v222 offset:49152
	ds_read_b128 v[164:167], v222 offset:50176
	ds_read_b128 v[168:171], v222 offset:51200
	ds_read_b128 v[172:175], v222 offset:52224
	ds_read_b128 v[196:199], v222 offset:53248
	ds_read_b128 v[200:203], v222 offset:54272
	ds_read_b128 v[204:207], v222 offset:55296
	ds_read_b128 v[224:227], v222 offset:56320
	global_load_lds_dwordx4 v[228:229], off
	s_add_i32 m0, s12, 0x2000
	s_add_u32 s0, s0, 0x40080
	v_lshl_add_u64 v[228:229], v[230:231], 0, s[26:27]
	s_addc_u32 s1, s1, 0
	s_add_i32 s12, s20, s4
	global_load_lds_dwordx4 v[228:229], off
	v_lshl_add_u64 v[228:229], s[0:1], 0, v[176:177]
	s_mov_b32 m0, s12
	s_nop 0
	global_load_lds_dwordx4 v[228:229], off
	v_lshl_add_u64 v[228:229], s[0:1], 0, v[190:191]
	s_add_i32 m0, s12, 0x2000
	s_nop 0
	global_load_lds_dwordx4 v[228:229], off
	v_lshl_add_u64 v[228:229], v[232:233], 0, s[26:27]
	s_mov_b32 m0, s9
	s_nop 0
	global_load_lds_dwordx4 v[228:229], off
	v_lshl_add_u64 v[228:229], v[234:235], 0, s[26:27]
	s_mov_b32 m0, s34
	s_nop 0
	global_load_lds_dwordx4 v[228:229], off
	s_waitcnt vmcnt(8)
	s_waitcnt lgkmcnt(0)
	s_barrier
	s_setprio 1
	s_waitcnt lgkmcnt(0)
	v_mfma_f32_16x16x32_bf16 v[60:63], v[128:131], v[160:163], v[60:63]
	v_mfma_f32_16x16x32_bf16 v[56:59], v[136:139], v[160:163], v[56:59]
	v_mfma_f32_16x16x32_bf16 v[44:47], v[128:131], v[168:171], v[44:47]
	v_mfma_f32_16x16x32_bf16 v[40:43], v[136:139], v[168:171], v[40:43]
	v_mfma_f32_16x16x32_bf16 v[28:31], v[128:131], v[196:199], v[28:31]
	v_mfma_f32_16x16x32_bf16 v[24:27], v[136:139], v[196:199], v[24:27]
	v_mfma_f32_16x16x32_bf16 v[12:15], v[128:131], v[204:207], v[12:15]
	v_mfma_f32_16x16x32_bf16 v[8:11], v[136:139], v[204:207], v[8:11]
	v_mfma_f32_16x16x32_bf16 v[60:63], v[132:135], v[164:167], v[60:63]
	v_mfma_f32_16x16x32_bf16 v[56:59], v[140:143], v[164:167], v[56:59]
	v_mfma_f32_16x16x32_bf16 v[44:47], v[132:135], v[172:175], v[44:47]
	v_mfma_f32_16x16x32_bf16 v[40:43], v[140:143], v[172:175], v[40:43]
	v_mfma_f32_16x16x32_bf16 v[28:31], v[132:135], v[200:203], v[28:31]
	v_mfma_f32_16x16x32_bf16 v[24:27], v[140:143], v[200:203], v[24:27]
	v_mfma_f32_16x16x32_bf16 v[12:15], v[132:135], v[224:227], v[12:15]
	v_mfma_f32_16x16x32_bf16 v[8:11], v[140:143], v[224:227], v[8:11]
	s_setprio 0
	s_setprio 1
	v_mfma_f32_16x16x32_bf16 v[52:55], v[144:147], v[160:163], v[52:55]
	v_mfma_f32_16x16x32_bf16 v[48:51], v[152:155], v[160:163], v[48:51]
	v_mfma_f32_16x16x32_bf16 v[36:39], v[144:147], v[168:171], v[36:39]
	v_mfma_f32_16x16x32_bf16 v[32:35], v[152:155], v[168:171], v[32:35]
	v_mfma_f32_16x16x32_bf16 v[20:23], v[144:147], v[196:199], v[20:23]
	v_mfma_f32_16x16x32_bf16 v[16:19], v[152:155], v[196:199], v[16:19]
	v_mfma_f32_16x16x32_bf16 v[4:7], v[144:147], v[204:207], v[4:7]
	v_mfma_f32_16x16x32_bf16 v[0:3], v[152:155], v[204:207], v[0:3]
	v_mfma_f32_16x16x32_bf16 v[52:55], v[148:151], v[164:167], v[52:55]
	v_mfma_f32_16x16x32_bf16 v[48:51], v[156:159], v[164:167], v[48:51]
	v_mfma_f32_16x16x32_bf16 v[36:39], v[148:151], v[172:175], v[36:39]
	v_mfma_f32_16x16x32_bf16 v[32:35], v[156:159], v[172:175], v[32:35]
	v_mfma_f32_16x16x32_bf16 v[20:23], v[148:151], v[200:203], v[20:23]
	v_mfma_f32_16x16x32_bf16 v[16:19], v[156:159], v[200:203], v[16:19]
	v_mfma_f32_16x16x32_bf16 v[4:7], v[148:151], v[224:227], v[4:7]
	v_mfma_f32_16x16x32_bf16 v[0:3], v[156:159], v[224:227], v[0:3]
	s_setprio 0
	s_barrier
	s_add_i32 s55, s55, 2
	s_add_u32 s72, s72, 0x100
	s_addc_u32 s73, s73, 0
	s_add_u32 s53, s53, 0x100
	s_addc_u32 s54, s54, 0
	s_cmp_gt_u32 s55, 13
	s_cbranch_scc0 .LBB0_719
	s_and_b64 vcc, exec, s[16:17]
	s_cbranch_vccz .LBB0_722
	s_barrier

; #define PG8_STAGE(bufoff, gbase, voff) do { _Pragma("unroll") for (int _i = 0; _i < 2; ++_i) \
;         __builtin_amdgcn_global_load_lds((const unsigned*)((const char*)(gbase) + (voff)[_i]), (PG8_LAS unsigned*)(lds + (bufoff) + ldsw + _i * 8192), 16, 0, 0); } while (0)
; #define PG8_WAIT_V(n) asm volatile("s_waitcnt vmcnt(" #n ")" ::: "memory")
; #define PG8_BAR __builtin_amdgcn_s_barrier()
; template <class Epi, class Sched, bool ALIGN_EPI = false, bool SP2 = false, bool TILED = false>
; __device__ __forceinline__ void gemm_phase(PG8_LAS unsigned char* lds, const Gemm g, const Sched& S, const Epi& E) {
;     ...
;     for (int i = 0; i < 2; ++i) { int R, C; stage_rc(tid * 16 + i * 8192, R, C); const int Rb = Epi::PERM ? ((R & ~31) + perm32(R & 31)) : R;
;         const int rs = TILED ? BK : K; voffA[i] = (unsigned)(R * rs + C) * 2u; voffB[i] = (unsigned)(Rb * rs + C) * 2u; }
;     const size_t kstep = TILED ? (size_t)(BM * BK * 2) : (size_t)(BK * 2);
;     const size_t hstep = TILED ? (size_t)(HALF * BK * 2) : (size_t)HALF * K * 2;
;     const size_t tstep = TILED ? (size_t)(K / BK) * (BM * BK * 2) : 2 * hstep;
;     const unsigned ldsw = (unsigned)wid * 1024u;
;     const int aoff = lds_byte(wr * 64 + fr, fq * 8), boff = lds_byte(wc * 32 + fr, fq * 8);
;     ...
;     Unit cur, nxt; int ui = 0;
;     if (!S.next(0, cur)) return;
;     f32x4 acc[2][2][4][2];
; #pragma unroll
;     for (int a = 0; a < 2; ++a)
; #pragma unroll
;         for (int b = 0; b < 2; ++b)
; #pragma unroll
;             for (int m = 0; m < 4; ++m)
; #pragma unroll
;                 for (int n = 0; n < 2; ++n) acc[a][b][m][n] = (f32x4){0.f, 0.f, 0.f, 0.f};
;     bf16x8 At[4][2], B0[2][2], B1[2][2];
;     const char* cA = (const char*)g.A + (size_t)cur.pm * tstep; const char* cB = (const char*)g.Bt + (size_t)cur.pn * tstep;
;     S.a_ready(cur);
;     if constexpr (SP2) {
;         PG8_STAGE(PG8_SB(0, 0), cB, voffB); PG8_STAGE(PG8_SB(0, 1), cB + hstep, voffB); PG8_STAGE(PG8_SA(0, 0), cA, voffA); PG8_STAGE(PG8_SA(0, 1), cA + hstep, voffA);
;         if (wr == 1) PG8_BAR;
;         PG8_WAIT_V(2); PG8_BAR;
;         PG8_STAGE(PG8_SB(1, 0), cB + kstep, voffB); PG8_STAGE(PG8_SA(1, 0), cA + kstep, voffA); PG8_STAGE(PG8_SB(1, 1), cB + hstep + kstep, voffB);
;         PG8_WAIT_V(6); PG8_BAR;
.LBB0_798:
	v_lshrrev_b32_e32 v16, 1, v6
	v_and_b32_e32 v16, 24, v16
	v_readlane_b32 s6, v250, 56
	v_and_b32_e32 v7, 15, v6
	v_lshlrev_b32_e32 v17, 1, v16
	v_lshlrev_b32_e32 v6, 2, v6
	s_lshl_b32 s1, s1, 5
	v_mov_b32_e32 v133, v177
	v_readlane_b32 s7, v250, 57
	v_lshl_or_b32 v148, s4, 6, v7
	v_lshl_or_b32 v7, v7, 6, v17
	s_lshl_b32 s4, s4, 13
	v_and_b32_e32 v6, 32, v6
	s_and_b32 s76, s1, 0x60
	v_lshl_add_u64 v[8:9], s[6:7], 0, v[132:133]
	v_mov_b32_e32 v129, v177
	v_readlane_b32 s18, v250, 52
	v_bitop3_b32 v17, v7, s4, v6 bitop3:0xde
	s_lshl_b32 s4, s76, 7
	v_lshl_add_u64 v[10:11], s[6:7], 0, v[128:129]
	v_mov_b32_e32 v135, v177
	v_readlane_b32 s19, v250, 53
	v_bitop3_b32 v149, v7, s4, v6 bitop3:0xde
	s_add_i32 m0, s40, 0x18000
	v_lshl_add_u64 v[6:7], v[8:9], 0, s[26:27]
	s_waitcnt vmcnt(0)
	v_lshl_add_u64 v[12:13], s[18:19], 0, v[134:135]
	v_mov_b32_e32 v131, v177
	s_waitcnt vmcnt(2)
	s_barrier
	global_load_lds_dwordx4 v[6:7], off
	v_lshl_add_u64 v[6:7], v[10:11], 0, s[26:27]
	s_add_i32 m0, s40, 0x1a000
	s_add_i32 s77, s40, 0x8000
	v_lshl_add_u64 v[14:15], s[18:19], 0, v[130:131]
	global_load_lds_dwordx4 v[6:7], off
	v_lshl_add_u64 v[6:7], v[12:13], 0, s[26:27]
	s_mov_b32 m0, s77
	s_add_i32 s78, s40, 0xa000
	v_readlane_b32 s4, v250, 58
	global_load_lds_dwordx4 v[6:7], off
	v_lshl_add_u64 v[6:7], v[14:15], 0, s[26:27]
	s_mov_b32 m0, s78
	v_readlane_b32 s5, v250, 59
	global_load_lds_dwordx4 v[6:7], off
	s_add_i32 m0, s40, 0x1c000
	v_lshl_add_u64 v[6:7], s[4:5], 0, v[132:133]
	global_load_lds_dwordx4 v[6:7], off
	v_lshl_add_u64 v[6:7], s[4:5], 0, v[128:129]
	s_add_i32 m0, s40, 0x1e000
	s_cmpk_lt_u32 s0, 0x100
	global_load_lds_dwordx4 v[6:7], off
	v_lshlrev_b32_e32 v7, 14, v4
	v_and_b32_e32 v7, 0xffff8000, v7
	v_lshl_add_u32 v3, v3, 11, v7
	v_and_b32_e32 v4, 1, v4
	v_lshl_or_b32 v3, v4, 6, v3
	v_lshl_add_u32 v136, v5, 1, v3
	v_lshlrev_b32_e32 v3, 14, v0
	v_and_b32_e32 v3, 0xffff8000, v3
	s_waitcnt vmcnt(0)
	v_and_or_b32 v6, s1, 32, v16
	v_lshl_add_u32 v1, v1, 11, v3
	v_and_b32_e32 v0, 1, v0
	v_readlane_b32 s0, v250, 46
	v_lshl_or_b32 v0, v0, 6, v1
	v_readlane_b32 s1, v250, 47
	s_cselect_b64 s[16:17], -1, 0
	v_mov_b32_e32 v137, v177
	v_lshl_add_u32 v138, v2, 1, v0
	v_mov_b32_e32 v139, v177
	s_mov_b32 s79, 0
	v_add_u32_e32 v150, 0, v17
	v_lshlrev_b32_e32 v140, 1, v6
	v_readlane_b32 s4, v250, 45
	s_mov_b32 s5, s0
	s_mov_b64 s[0:1], s[6:7]
	s_barrier
	s_branch .LBB0_801

; #define PG8_STAGE(bufoff, gbase, voff) do { _Pragma("unroll") for (int _i = 0; _i < 2; ++_i) \
;         __builtin_amdgcn_global_load_lds((const unsigned*)((const char*)(gbase) + (voff)[_i]), (PG8_LAS unsigned*)(lds + (bufoff) + ldsw + _i * 8192), 16, 0, 0); } while (0)
; #define PG8_LDA(dst, b, h) do { _Pragma("unroll") for (int m = 0; m < 4; ++m) _Pragma("unroll") for (int k = 0; k < 2; ++k) dst[m][k] = *(const PG8_LAS bf16x8*)(lds + PG8_SA(b, h) + aoff + m * 2048 + k * 1024); } while (0)
; #define PG8_LDB(dst, b, h) do { _Pragma("unroll") for (int n = 0; n < 2; ++n) _Pragma("unroll") for (int k = 0; k < 2; ++k) dst[n][k] = *(const PG8_LAS bf16x8*)(lds + PG8_SB(b, h) + boff + n * 2048 + k * 1024); } while (0)
; #define PG8_MMA(ai, bj, At, Bt) do { __builtin_amdgcn_s_setprio(1); _Pragma("unroll") for (int m = 0; m < 4; ++m) _Pragma("unroll") for (int n = 0; n < 2; ++n) _Pragma("unroll") for (int k = 0; k < 2; ++k) \
;         acc[ai][bj][m][n] = __builtin_amdgcn_mfma_f32_16x16x32_bf16(Bt[n][k], At[m][k], acc[ai][bj][m][n], 0, 0, 0); __builtin_amdgcn_s_setprio(0); } while (0)
; #define PG8_WAIT_V(n) asm volatile("s_waitcnt vmcnt(" #n ")" ::: "memory")
; #define PG8_WAIT_L(n) asm volatile("s_waitcnt lgkmcnt(" #n ")" ::: "memory")
; #define PG8_BAR __builtin_amdgcn_s_barrier()
; #define PG8_SCHED __builtin_amdgcn_sched_barrier(0)
; template <class Epi, class Sched, bool ALIGN_EPI = false, bool SP2 = false, bool TILED = false>
; __device__ __forceinline__ void gemm_phase(PG8_LAS unsigned char* lds, const Gemm g, const Sched& S, const Epi& E) {
;     ...
;             PG8_LDB(B0, 0, 0); PG8_LDB(B1, 0, 1); PG8_SCHED; PG8_LDA(At, 0, 0); PG8_STAGE(PG8_SA(1, 1), a1 + hstep, voffA);
;             PG8_WAIT_V(8); PG8_WAIT_L(0); PG8_BAR; PG8_MMA(0, 0, At, B0); PG8_MMA(0, 1, At, B1); PG8_BAR; PG8_SCHED;
;             PG8_LDA(At, 0, 1); PG8_STAGE(PG8_SB(0, 0), b2, voffB); PG8_STAGE(PG8_SB(0, 1), b2 + hstep, voffB); PG8_STAGE(PG8_SA(0, 0), a2, voffA);
.LBB0_808:
	s_add_u32 s0, s64, 0xfffc0080
	s_addc_u32 s1, s65, -1
	s_add_i32 s12, 0, 0x10000
	s_cmp_eq_u32 s38, 12
	s_cselect_b32 s19, s6, s1
	s_cselect_b32 s18, s7, s0
	v_add_u32_e32 v141, s12, v149
	s_cselect_b32 s1, s8, s11
	s_cselect_b32 s0, s9, s10
	s_add_i32 s35, 0, 0x14000
	ds_read_b128 v[142:145], v141
	ds_read_b128 v[152:155], v141 offset:1024
	ds_read_b128 v[156:159], v141 offset:2048
	ds_read_b128 v[160:163], v141 offset:3072
	v_add_u32_e32 v141, s35, v149
	ds_read_b128 v[164:167], v141
	ds_read_b128 v[168:171], v141 offset:1024
	ds_read_b128 v[172:175], v141 offset:2048
	ds_read_b128 v[190:193], v141 offset:3072
	v_lshl_add_u64 v[146:147], s[64:65], 0, v[136:137]
	s_add_i32 m0, s40, 0xc000
	ds_read_b128 v[194:197], v150
	ds_read_b128 v[198:201], v150 offset:1024
	ds_read_b128 v[202:205], v150 offset:2048
	ds_read_b128 v[220:223], v150 offset:3072
	ds_read_b128 v[224:227], v150 offset:4096
	ds_read_b128 v[228:231], v150 offset:5120
	ds_read_b128 v[232:235], v150 offset:6144
	ds_read_b128 v[236:239], v150 offset:7168
	global_load_lds_dwordx4 v[146:147], off
	v_lshl_add_u64 v[146:147], s[64:65], 0, v[138:139]
	s_add_i32 m0, s40, 0xe000
	s_nop 0
	global_load_lds_dwordx4 v[146:147], off
	s_cmp_eq_u32 s38, -2
	s_cbranch_scc1 .Lmyw_6
	s_waitcnt vmcnt(8)
.Lmyw_6:
	s_waitcnt lgkmcnt(0)
	s_barrier
	s_setprio 1
	s_waitcnt lgkmcnt(0)
	v_mfma_f32_16x16x32_bf16 v[124:127], v[142:145], v[194:197], v[124:127]
	v_mfma_f32_16x16x32_bf16 v[120:123], v[156:159], v[194:197], v[120:123]
	v_mfma_f32_16x16x32_bf16 v[108:111], v[142:145], v[202:205], v[108:111]
	v_mfma_f32_16x16x32_bf16 v[104:107], v[156:159], v[202:205], v[104:107]
	v_mfma_f32_16x16x32_bf16 v[92:95], v[142:145], v[224:227], v[92:95]
	v_mfma_f32_16x16x32_bf16 v[88:91], v[156:159], v[224:227], v[88:91]
	v_mfma_f32_16x16x32_bf16 v[76:79], v[142:145], v[232:235], v[76:79]
	v_mfma_f32_16x16x32_bf16 v[72:75], v[156:159], v[232:235], v[72:75]
	v_mfma_f32_16x16x32_bf16 v[124:127], v[152:155], v[198:201], v[124:127]
	v_mfma_f32_16x16x32_bf16 v[120:123], v[160:163], v[198:201], v[120:123]
	v_mfma_f32_16x16x32_bf16 v[108:111], v[152:155], v[220:223], v[108:111]
	v_mfma_f32_16x16x32_bf16 v[104:107], v[160:163], v[220:223], v[104:107]
	v_mfma_f32_16x16x32_bf16 v[92:95], v[152:155], v[228:231], v[92:95]
	v_mfma_f32_16x16x32_bf16 v[88:91], v[160:163], v[228:231], v[88:91]
	v_mfma_f32_16x16x32_bf16 v[76:79], v[152:155], v[236:239], v[76:79]
	v_mfma_f32_16x16x32_bf16 v[72:75], v[160:163], v[236:239], v[72:75]
	s_setprio 0
	s_setprio 1
	v_mfma_f32_16x16x32_bf16 v[116:119], v[164:167], v[194:197], v[116:119]
	v_mfma_f32_16x16x32_bf16 v[112:115], v[172:175], v[194:197], v[112:115]
	v_mfma_f32_16x16x32_bf16 v[100:103], v[164:167], v[202:205], v[100:103]
	v_mfma_f32_16x16x32_bf16 v[96:99], v[172:175], v[202:205], v[96:99]
	v_mfma_f32_16x16x32_bf16 v[84:87], v[164:167], v[224:227], v[84:87]
	v_mfma_f32_16x16x32_bf16 v[80:83], v[172:175], v[224:227], v[80:83]
	v_mfma_f32_16x16x32_bf16 v[68:71], v[164:167], v[232:235], v[68:71]
	v_mfma_f32_16x16x32_bf16 v[64:67], v[172:175], v[232:235], v[64:67]
	v_mfma_f32_16x16x32_bf16 v[116:119], v[168:171], v[198:201], v[116:119]
	v_mfma_f32_16x16x32_bf16 v[112:115], v[190:193], v[198:201], v[112:115]
	v_mfma_f32_16x16x32_bf16 v[100:103], v[168:171], v[220:223], v[100:103]
	v_mfma_f32_16x16x32_bf16 v[96:99], v[190:193], v[220:223], v[96:99]
	v_mfma_f32_16x16x32_bf16 v[84:87], v[168:171], v[228:231], v[84:87]
	v_mfma_f32_16x16x32_bf16 v[80:83], v[190:193], v[228:231], v[80:83]
	v_mfma_f32_16x16x32_bf16 v[68:71], v[168:171], v[236:239], v[68:71]
	v_mfma_f32_16x16x32_bf16 v[64:67], v[190:193], v[236:239], v[64:67]
	s_setprio 0
	s_barrier
	s_add_i32 s12, s12, s34
	v_lshl_add_u64 v[146:147], s[0:1], 0, v[132:133]
	s_mov_b32 m0, s12
	ds_read_b128 v[194:197], v150 offset:16384
	ds_read_b128 v[198:201], v150 offset:17408
	ds_read_b128 v[202:205], v150 offset:18432
	ds_read_b128 v[220:223], v150 offset:19456
	ds_read_b128 v[224:227], v150 offset:20480
	ds_read_b128 v[228:231], v150 offset:21504
	ds_read_b128 v[232:235], v150 offset:22528
	ds_read_b128 v[236:239], v150 offset:23552
	global_load_lds_dwordx4 v[146:147], off
	s_add_i32 m0, s12, 0x2000
	s_add_u32 s20, s0, 0x40000
	v_lshl_add_u64 v[206:207], s[0:1], 0, v[128:129]
	s_addc_u32 s21, s1, 0
	s_add_i32 s12, s35, s34
	global_load_lds_dwordx4 v[206:207], off
	v_lshl_add_u64 v[240:241], s[20:21], 0, v[132:133]
	s_mov_b32 m0, s12
	v_lshl_add_u64 v[242:243], s[18:19], 0, v[130:131]
	global_load_lds_dwordx4 v[240:241], off
	v_lshl_add_u64 v[240:241], s[20:21], 0, v[128:129]
	s_add_i32 m0, s12, 0x2000
	s_nop 0
	global_load_lds_dwordx4 v[240:241], off
	v_lshl_add_u64 v[240:241], s[18:19], 0, v[134:135]
	s_mov_b32 m0, s40
	s_nop 0
	global_load_lds_dwordx4 v[240:241], off
	s_mov_b32 m0, s41
	s_nop 0
	global_load_lds_dwordx4 v[242:243], off
	s_cmp_eq_u32 s38, -2
	s_cbranch_scc1 .Lmyw_7
	s_waitcnt vmcnt(8)
; #define PG8_STAGE(bufoff, gbase, voff) do { _Pragma("unroll") for (int _i = 0; _i < 2; ++_i) \
;         __builtin_amdgcn_global_load_lds((const unsigned*)((const char*)(gbase) + (voff)[_i]), (PG8_LAS unsigned*)(lds + (bufoff) + ldsw + _i * 8192), 16, 0, 0); } while (0)
; #define PG8_LDA(dst, b, h) do { _Pragma("unroll") for (int m = 0; m < 4; ++m) _Pragma("unroll") for (int k = 0; k < 2; ++k) dst[m][k] = *(const PG8_LAS bf16x8*)(lds + PG8_SA(b, h) + aoff + m * 2048 + k * 1024); } while (0)
; #define PG8_LDB(dst, b, h) do { _Pragma("unroll") for (int n = 0; n < 2; ++n) _Pragma("unroll") for (int k = 0; k < 2; ++k) dst[n][k] = *(const PG8_LAS bf16x8*)(lds + PG8_SB(b, h) + boff + n * 2048 + k * 1024); } while (0)
; #define PG8_MMA(ai, bj, At, Bt) do { __builtin_amdgcn_s_setprio(1); _Pragma("unroll") for (int m = 0; m < 4; ++m) _Pragma("unroll") for (int n = 0; n < 2; ++n) _Pragma("unroll") for (int k = 0; k < 2; ++k) \
;         acc[ai][bj][m][n] = __builtin_amdgcn_mfma_f32_16x16x32_bf16(Bt[n][k], At[m][k], acc[ai][bj][m][n], 0, 0, 0); __builtin_amdgcn_s_setprio(0); } while (0)
; #define PG8_WAIT_V(n) asm volatile("s_waitcnt vmcnt(" #n ")" ::: "memory")
; #define PG8_WAIT_L(n) asm volatile("s_waitcnt lgkmcnt(" #n ")" ::: "memory")
; #define PG8_BAR __builtin_amdgcn_s_barrier()
; #define PG8_SCHED __builtin_amdgcn_sched_barrier(0)
; template <class Epi, class Sched, bool ALIGN_EPI = false, bool SP2 = false, bool TILED = false>
; __device__ __forceinline__ void gemm_phase(PG8_LAS unsigned char* lds, const Gemm g, const Sched& S, const Epi& E) {
;     ...
;             PG8_WAIT_V(8); PG8_WAIT_L(0); PG8_BAR; PG8_MMA(1, 0, At, B0); PG8_MMA(1, 1, At, B1); PG8_BAR; PG8_SCHED;
;             PG8_LDB(B0, 1, 0); PG8_LDB(B1, 1, 1); PG8_SCHED; PG8_LDA(At, 1, 0); PG8_STAGE(PG8_SA(0, 1), a2 + hstep, voffA);
;             PG8_WAIT_V(8); PG8_WAIT_L(0); PG8_BAR; PG8_MMA(0, 0, At, B0); PG8_MMA(0, 1, At, B1); PG8_BAR; PG8_SCHED;
.Lmyw_7:
	s_waitcnt lgkmcnt(0)
	s_barrier
	s_setprio 1
	s_waitcnt lgkmcnt(0)
	v_mfma_f32_16x16x32_bf16 v[60:63], v[142:145], v[194:197], v[60:63]
	v_mfma_f32_16x16x32_bf16 v[56:59], v[156:159], v[194:197], v[56:59]
	v_mfma_f32_16x16x32_bf16 v[44:47], v[142:145], v[202:205], v[44:47]
	v_mfma_f32_16x16x32_bf16 v[40:43], v[156:159], v[202:205], v[40:43]
	v_mfma_f32_16x16x32_bf16 v[28:31], v[142:145], v[224:227], v[28:31]
	v_mfma_f32_16x16x32_bf16 v[24:27], v[156:159], v[224:227], v[24:27]
	v_mfma_f32_16x16x32_bf16 v[12:15], v[142:145], v[232:235], v[12:15]
	v_mfma_f32_16x16x32_bf16 v[8:11], v[156:159], v[232:235], v[8:11]
	v_mfma_f32_16x16x32_bf16 v[60:63], v[152:155], v[198:201], v[60:63]
	v_mfma_f32_16x16x32_bf16 v[56:59], v[160:163], v[198:201], v[56:59]
	v_mfma_f32_16x16x32_bf16 v[44:47], v[152:155], v[220:223], v[44:47]
	v_mfma_f32_16x16x32_bf16 v[40:43], v[160:163], v[220:223], v[40:43]
	v_mfma_f32_16x16x32_bf16 v[28:31], v[152:155], v[228:231], v[28:31]
	v_mfma_f32_16x16x32_bf16 v[24:27], v[160:163], v[228:231], v[24:27]
	v_mfma_f32_16x16x32_bf16 v[12:15], v[152:155], v[236:239], v[12:15]
	v_mfma_f32_16x16x32_bf16 v[8:11], v[160:163], v[236:239], v[8:11]
	s_setprio 0
	s_setprio 1
	v_mfma_f32_16x16x32_bf16 v[52:55], v[164:167], v[194:197], v[52:55]
	v_mfma_f32_16x16x32_bf16 v[48:51], v[172:175], v[194:197], v[48:51]
	v_mfma_f32_16x16x32_bf16 v[36:39], v[164:167], v[202:205], v[36:39]
	v_mfma_f32_16x16x32_bf16 v[32:35], v[172:175], v[202:205], v[32:35]
	v_mfma_f32_16x16x32_bf16 v[20:23], v[164:167], v[224:227], v[20:23]
	v_mfma_f32_16x16x32_bf16 v[16:19], v[172:175], v[224:227], v[16:19]
	v_mfma_f32_16x16x32_bf16 v[4:7], v[164:167], v[232:235], v[4:7]
	v_mfma_f32_16x16x32_bf16 v[0:3], v[172:175], v[232:235], v[0:3]
	v_mfma_f32_16x16x32_bf16 v[52:55], v[168:171], v[198:201], v[52:55]
	v_mfma_f32_16x16x32_bf16 v[48:51], v[190:193], v[198:201], v[48:51]
	v_mfma_f32_16x16x32_bf16 v[36:39], v[168:171], v[220:223], v[36:39]
	v_mfma_f32_16x16x32_bf16 v[32:35], v[190:193], v[220:223], v[32:35]
	v_mfma_f32_16x16x32_bf16 v[20:23], v[168:171], v[228:231], v[20:23]
	v_mfma_f32_16x16x32_bf16 v[16:19], v[190:193], v[228:231], v[16:19]
	v_mfma_f32_16x16x32_bf16 v[4:7], v[168:171], v[236:239], v[4:7]
	v_mfma_f32_16x16x32_bf16 v[0:3], v[190:193], v[236:239], v[0:3]
	s_setprio 0
	s_barrier
	s_add_i32 s12, 0, 0x18000
	v_add_u32_e32 v141, s12, v149
	s_add_i32 s20, 0, 0x1c000
	ds_read_b128 v[142:145], v141
	ds_read_b128 v[152:155], v141 offset:1024
	ds_read_b128 v[156:159], v141 offset:2048
	ds_read_b128 v[160:163], v141 offset:3072
	v_add_u32_e32 v141, s20, v149
	ds_read_b128 v[164:167], v141
	ds_read_b128 v[168:171], v141 offset:1024
	ds_read_b128 v[172:175], v141 offset:2048
	ds_read_b128 v[190:193], v141 offset:3072
	s_add_u32 s18, s18, 0x40000
	s_addc_u32 s19, s19, 0
	s_mov_b32 m0, s72
	v_lshl_add_u64 v[244:245], s[18:19], 0, v[134:135]
	ds_read_b128 v[194:197], v150 offset:32768
	ds_read_b128 v[198:201], v150 offset:33792
	ds_read_b128 v[202:205], v150 offset:34816
	ds_read_b128 v[220:223], v150 offset:35840
	ds_read_b128 v[224:227], v150 offset:36864
	ds_read_b128 v[228:231], v150 offset:37888
	ds_read_b128 v[232:235], v150 offset:38912
	ds_read_b128 v[236:239], v150 offset:39936
	global_load_lds_dwordx4 v[244:245], off
	v_lshl_add_u64 v[244:245], s[18:19], 0, v[130:131]
	s_mov_b32 m0, s73
	s_nop 0
	global_load_lds_dwordx4 v[244:245], off
	s_waitcnt vmcnt(8)
	s_waitcnt lgkmcnt(0)
	s_barrier
	s_setprio 1
	s_waitcnt lgkmcnt(0)
	v_mfma_f32_16x16x32_bf16 v[124:127], v[142:145], v[194:197], v[124:127]
	v_mfma_f32_16x16x32_bf16 v[120:123], v[156:159], v[194:197], v[120:123]
	v_mfma_f32_16x16x32_bf16 v[108:111], v[142:145], v[202:205], v[108:111]
	v_mfma_f32_16x16x32_bf16 v[104:107], v[156:159], v[202:205], v[104:107]
	v_mfma_f32_16x16x32_bf16 v[92:95], v[142:145], v[224:227], v[92:95]
	v_mfma_f32_16x16x32_bf16 v[88:91], v[156:159], v[224:227], v[88:91]
	v_mfma_f32_16x16x32_bf16 v[76:79], v[142:145], v[232:235], v[76:79]
	v_mfma_f32_16x16x32_bf16 v[72:75], v[156:159], v[232:235], v[72:75]
	v_mfma_f32_16x16x32_bf16 v[124:127], v[152:155], v[198:201], v[124:127]
	v_mfma_f32_16x16x32_bf16 v[120:123], v[160:163], v[198:201], v[120:123]
	v_mfma_f32_16x16x32_bf16 v[108:111], v[152:155], v[220:223], v[108:111]
	v_mfma_f32_16x16x32_bf16 v[104:107], v[160:163], v[220:223], v[104:107]
	v_mfma_f32_16x16x32_bf16 v[92:95], v[152:155], v[228:231], v[92:95]
	v_mfma_f32_16x16x32_bf16 v[88:91], v[160:163], v[228:231], v[88:91]
	v_mfma_f32_16x16x32_bf16 v[76:79], v[152:155], v[236:239], v[76:79]
	v_mfma_f32_16x16x32_bf16 v[72:75], v[160:163], v[236:239], v[72:75]
	s_setprio 0
	s_setprio 1
	v_mfma_f32_16x16x32_bf16 v[116:119], v[164:167], v[194:197], v[116:119]
	v_mfma_f32_16x16x32_bf16 v[112:115], v[172:175], v[194:197], v[112:115]
	v_mfma_f32_16x16x32_bf16 v[100:103], v[164:167], v[202:205], v[100:103]
	v_mfma_f32_16x16x32_bf16 v[96:99], v[172:175], v[202:205], v[96:99]
	v_mfma_f32_16x16x32_bf16 v[84:87], v[164:167], v[224:227], v[84:87]
	v_mfma_f32_16x16x32_bf16 v[80:83], v[172:175], v[224:227], v[80:83]
	v_mfma_f32_16x16x32_bf16 v[68:71], v[164:167], v[232:235], v[68:71]
	v_mfma_f32_16x16x32_bf16 v[64:67], v[172:175], v[232:235], v[64:67]
	v_mfma_f32_16x16x32_bf16 v[116:119], v[168:171], v[198:201], v[116:119]
	v_mfma_f32_16x16x32_bf16 v[112:115], v[190:193], v[198:201], v[112:115]
	v_mfma_f32_16x16x32_bf16 v[100:103], v[168:171], v[220:223], v[100:103]
	v_mfma_f32_16x16x32_bf16 v[96:99], v[190:193], v[220:223], v[96:99]
	v_mfma_f32_16x16x32_bf16 v[84:87], v[168:171], v[228:231], v[84:87]
	v_mfma_f32_16x16x32_bf16 v[80:83], v[190:193], v[228:231], v[80:83]
	v_mfma_f32_16x16x32_bf16 v[68:71], v[168:171], v[236:239], v[68:71]
	v_mfma_f32_16x16x32_bf16 v[64:67], v[190:193], v[236:239], v[64:67]
	s_setprio 0
	s_barrier
; #define PG8_STAGE(bufoff, gbase, voff) do { _Pragma("unroll") for (int _i = 0; _i < 2; ++_i) \
;         __builtin_amdgcn_global_load_lds((const unsigned*)((const char*)(gbase) + (voff)[_i]), (PG8_LAS unsigned*)(lds + (bufoff) + ldsw + _i * 8192), 16, 0, 0); } while (0)
; #define PG8_LDA(dst, b, h) do { _Pragma("unroll") for (int m = 0; m < 4; ++m) _Pragma("unroll") for (int k = 0; k < 2; ++k) dst[m][k] = *(const PG8_LAS bf16x8*)(lds + PG8_SA(b, h) + aoff + m * 2048 + k * 1024); } while (0)
; #define PG8_MMA(ai, bj, At, Bt) do { __builtin_amdgcn_s_setprio(1); _Pragma("unroll") for (int m = 0; m < 4; ++m) _Pragma("unroll") for (int n = 0; n < 2; ++n) _Pragma("unroll") for (int k = 0; k < 2; ++k) \
;         acc[ai][bj][m][n] = __builtin_amdgcn_mfma_f32_16x16x32_bf16(Bt[n][k], At[m][k], acc[ai][bj][m][n], 0, 0, 0); __builtin_amdgcn_s_setprio(0); } while (0)
; #define PG8_WAIT_V(n) asm volatile("s_waitcnt vmcnt(" #n ")" ::: "memory")
; #define PG8_WAIT_L(n) asm volatile("s_waitcnt lgkmcnt(" #n ")" ::: "memory")
; #define PG8_BAR __builtin_amdgcn_s_barrier()
; #define PG8_SCHED __builtin_amdgcn_sched_barrier(0)
; template <class Epi, class Sched, bool ALIGN_EPI = false, bool SP2 = false, bool TILED = false>
; __device__ __forceinline__ void gemm_phase(PG8_LAS unsigned char* lds, const Gemm g, const Sched& S, const Epi& E) {
;     ...
;             PG8_LDA(At, 1, 1); PG8_STAGE(PG8_SB(1, 0), b3, voffB); PG8_STAGE(PG8_SB(1, 1), b3 + hstep, voffB); PG8_STAGE(PG8_SA(1, 0), a3, voffA);
;             PG8_WAIT_V(8); PG8_WAIT_L(0); PG8_BAR; PG8_MMA(1, 0, At, B0); PG8_MMA(1, 1, At, B1); PG8_BAR; PG8_SCHED;
	s_add_i32 s12, s12, s34
	v_lshl_add_u64 v[146:147], v[146:147], 0, s[26:27]
	s_mov_b32 m0, s12
	ds_read_b128 v[194:197], v150 offset:49152
	ds_read_b128 v[198:201], v150 offset:50176
	ds_read_b128 v[202:205], v150 offset:51200
	ds_read_b128 v[220:223], v150 offset:52224
	ds_read_b128 v[224:227], v150 offset:53248
	ds_read_b128 v[228:231], v150 offset:54272
	ds_read_b128 v[232:235], v150 offset:55296
	ds_read_b128 v[236:239], v150 offset:56320
	global_load_lds_dwordx4 v[146:147], off
	s_add_i32 m0, s12, 0x2000
	s_add_u32 s0, s0, 0x40080
	v_lshl_add_u64 v[146:147], v[206:207], 0, s[26:27]
	s_addc_u32 s1, s1, 0
	s_add_i32 s12, s20, s34
	global_load_lds_dwordx4 v[146:147], off
	v_lshl_add_u64 v[146:147], s[0:1], 0, v[132:133]
	s_mov_b32 m0, s12
	s_nop 0
	global_load_lds_dwordx4 v[146:147], off
	v_lshl_add_u64 v[146:147], s[0:1], 0, v[128:129]
	s_add_i32 m0, s12, 0x2000
	s_nop 0
	global_load_lds_dwordx4 v[146:147], off
	v_lshl_add_u64 v[146:147], v[240:241], 0, s[26:27]
	s_mov_b32 m0, s77
	s_nop 0
	global_load_lds_dwordx4 v[146:147], off
	v_lshl_add_u64 v[146:147], v[242:243], 0, s[26:27]
	s_mov_b32 m0, s78
	s_nop 0
	global_load_lds_dwordx4 v[146:147], off
	s_waitcnt vmcnt(8)
	s_waitcnt lgkmcnt(0)
	s_barrier
	s_setprio 1
	s_waitcnt lgkmcnt(0)
	v_mfma_f32_16x16x32_bf16 v[60:63], v[142:145], v[194:197], v[60:63]
	v_mfma_f32_16x16x32_bf16 v[56:59], v[156:159], v[194:197], v[56:59]
	v_mfma_f32_16x16x32_bf16 v[44:47], v[142:145], v[202:205], v[44:47]
	v_mfma_f32_16x16x32_bf16 v[40:43], v[156:159], v[202:205], v[40:43]
	v_mfma_f32_16x16x32_bf16 v[28:31], v[142:145], v[224:227], v[28:31]
	v_mfma_f32_16x16x32_bf16 v[24:27], v[156:159], v[224:227], v[24:27]
	v_mfma_f32_16x16x32_bf16 v[12:15], v[142:145], v[232:235], v[12:15]
	v_mfma_f32_16x16x32_bf16 v[8:11], v[156:159], v[232:235], v[8:11]
	v_mfma_f32_16x16x32_bf16 v[60:63], v[152:155], v[198:201], v[60:63]
	v_mfma_f32_16x16x32_bf16 v[56:59], v[160:163], v[198:201], v[56:59]
	v_mfma_f32_16x16x32_bf16 v[44:47], v[152:155], v[220:223], v[44:47]
	v_mfma_f32_16x16x32_bf16 v[40:43], v[160:163], v[220:223], v[40:43]
	v_mfma_f32_16x16x32_bf16 v[28:31], v[152:155], v[228:231], v[28:31]
	v_mfma_f32_16x16x32_bf16 v[24:27], v[160:163], v[228:231], v[24:27]
	v_mfma_f32_16x16x32_bf16 v[12:15], v[152:155], v[236:239], v[12:15]
	v_mfma_f32_16x16x32_bf16 v[8:11], v[160:163], v[236:239], v[8:11]
	s_setprio 0
	s_setprio 1
	v_mfma_f32_16x16x32_bf16 v[52:55], v[164:167], v[194:197], v[52:55]
	v_mfma_f32_16x16x32_bf16 v[48:51], v[172:175], v[194:197], v[48:51]
	v_mfma_f32_16x16x32_bf16 v[36:39], v[164:167], v[202:205], v[36:39]
	v_mfma_f32_16x16x32_bf16 v[32:35], v[172:175], v[202:205], v[32:35]
	v_mfma_f32_16x16x32_bf16 v[20:23], v[164:167], v[224:227], v[20:23]
	v_mfma_f32_16x16x32_bf16 v[16:19], v[172:175], v[224:227], v[16:19]
	v_mfma_f32_16x16x32_bf16 v[4:7], v[164:167], v[232:235], v[4:7]
	v_mfma_f32_16x16x32_bf16 v[0:3], v[172:175], v[232:235], v[0:3]
	v_mfma_f32_16x16x32_bf16 v[52:55], v[168:171], v[198:201], v[52:55]
	v_mfma_f32_16x16x32_bf16 v[48:51], v[190:193], v[198:201], v[48:51]
	v_mfma_f32_16x16x32_bf16 v[36:39], v[168:171], v[220:223], v[36:39]
	v_mfma_f32_16x16x32_bf16 v[32:35], v[190:193], v[220:223], v[32:35]
	v_mfma_f32_16x16x32_bf16 v[20:23], v[168:171], v[228:231], v[20:23]
	v_mfma_f32_16x16x32_bf16 v[16:19], v[190:193], v[228:231], v[16:19]
	v_mfma_f32_16x16x32_bf16 v[4:7], v[168:171], v[236:239], v[4:7]
	v_mfma_f32_16x16x32_bf16 v[0:3], v[190:193], v[236:239], v[0:3]
	s_setprio 0
	s_barrier
	s_add_i32 s38, s38, 2
	s_add_u32 s64, s64, 0x100
	s_addc_u32 s65, s65, 0
	s_add_u32 s10, s10, 0x100
	s_addc_u32 s11, s11, 0
	s_cmp_gt_u32 s38, 13
	s_cbranch_scc0 .LBB0_808
	s_and_b64 vcc, exec, s[16:17]
	s_cbranch_vccz .LBB0_811
	s_barrier

; #define PG8_STAGE(bufoff, gbase, voff) do { _Pragma("unroll") for (int _i = 0; _i < 2; ++_i) \
;         __builtin_amdgcn_global_load_lds((const unsigned*)((const char*)(gbase) + (voff)[_i]), (PG8_LAS unsigned*)(lds + (bufoff) + ldsw + _i * 8192), 16, 0, 0); } while (0)
; #define PG8_WAIT_V(n) asm volatile("s_waitcnt vmcnt(" #n ")" ::: "memory")
; #define PG8_BAR __builtin_amdgcn_s_barrier()
; template <class Epi, class Sched, bool ALIGN_EPI = false, bool SP2 = false, bool TILED = false>
; __device__ __forceinline__ void gemm_phase(PG8_LAS unsigned char* lds, const Gemm g, const Sched& S, const Epi& E) {
;     ...
;     for (int i = 0; i < 2; ++i) { int R, C; stage_rc(tid * 16 + i * 8192, R, C); const int Rb = Epi::PERM ? ((R & ~31) + perm32(R & 31)) : R;
;         const int rs = TILED ? BK : K; voffA[i] = (unsigned)(R * rs + C) * 2u; voffB[i] = (unsigned)(Rb * rs + C) * 2u; }
;     const size_t kstep = TILED ? (size_t)(BM * BK * 2) : (size_t)(BK * 2);
;     const size_t hstep = TILED ? (size_t)(HALF * BK * 2) : (size_t)HALF * K * 2;
;     const size_t tstep = TILED ? (size_t)(K / BK) * (BM * BK * 2) : 2 * hstep;
;     const unsigned ldsw = (unsigned)wid * 1024u;
;     const int aoff = lds_byte(wr * 64 + fr, fq * 8), boff = lds_byte(wc * 32 + fr, fq * 8);
;     ...
;     Unit cur, nxt; int ui = 0;
;     if (!S.next(0, cur)) return;
;     f32x4 acc[2][2][4][2];
; #pragma unroll
;     for (int a = 0; a < 2; ++a)
; #pragma unroll
;         for (int b = 0; b < 2; ++b)
; #pragma unroll
;             for (int m = 0; m < 4; ++m)
; #pragma unroll
;                 for (int n = 0; n < 2; ++n) acc[a][b][m][n] = (f32x4){0.f, 0.f, 0.f, 0.f};
;     bf16x8 At[4][2], B0[2][2], B1[2][2];
;     const char* cA = (const char*)g.A + (size_t)cur.pm * tstep; const char* cB = (const char*)g.Bt + (size_t)cur.pn * tstep;
;     S.a_ready(cur);
;     if constexpr (SP2) {
;         PG8_STAGE(PG8_SB(0, 0), cB, voffB); PG8_STAGE(PG8_SB(0, 1), cB + hstep, voffB); PG8_STAGE(PG8_SA(0, 0), cA, voffA); PG8_STAGE(PG8_SA(0, 1), cA + hstep, voffA);
;         if (wr == 1) PG8_BAR;
;         PG8_WAIT_V(2); PG8_BAR;
;         PG8_STAGE(PG8_SB(1, 0), cB + kstep, voffB); PG8_STAGE(PG8_SA(1, 0), cA + kstep, voffA); PG8_STAGE(PG8_SB(1, 1), cB + hstep + kstep, voffB);
;         PG8_WAIT_V(6); PG8_BAR;
.LBB0_869:
	v_readlane_b32 s18, v249, 60
	v_readlane_b32 s19, v249, 61
	s_lshl_b32 s12, s18, 8
	s_lshl_b64 s[18:19], s[12:13], 2
	v_readlane_b32 s9, v250, 27
	s_add_u32 s9, s9, s18
	v_readlane_b32 s11, v250, 28
	s_addc_u32 s34, s11, s19
	s_lshl_b32 s1, s1, 5
	s_and_b32 s1, s1, 0x60
	s_lshl_b32 s11, s10, 13
	s_lshl_b32 s12, s1, 7
	v_readlane_b32 s18, v251, 7
	v_readlane_b32 s20, v249, 27
	s_add_u32 s18, s18, s46
	v_readlane_b32 s19, v251, 8
	v_readlane_b32 s21, v249, 28
	v_mov_b32_e32 v129, v177
	s_addc_u32 s19, s19, s47
	s_add_i32 m0, s5, 0x18000
	v_lshl_add_u64 v[8:9], s[20:21], 0, v[176:177]
	s_waitcnt vmcnt(2)
	s_barrier
	global_load_lds_dwordx4 v[8:9], off
	v_lshl_add_u64 v[8:9], s[20:21], 0, v[128:129]
	v_readlane_b32 s20, v249, 31
	s_add_i32 m0, s5, 0x1a000
	v_readlane_b32 s21, v249, 32
	s_add_i32 s54, s5, 0x8000
	global_load_lds_dwordx4 v[8:9], off
	v_lshl_add_u64 v[8:9], s[20:21], 0, v[176:177]
	s_mov_b32 m0, s54
	s_add_i32 s55, s5, 0xa000
	global_load_lds_dwordx4 v[8:9], off
	v_lshl_add_u64 v[8:9], s[20:21], 0, v[128:129]
	v_readlane_b32 s20, v249, 35
	s_mov_b32 m0, s55
	v_readlane_b32 s21, v249, 36
	global_load_lds_dwordx4 v[8:9], off
	s_add_i32 m0, s5, 0x1c000
	v_lshl_add_u64 v[8:9], s[20:21], 0, v[176:177]
	global_load_lds_dwordx4 v[8:9], off
	v_lshl_add_u64 v[8:9], s[20:21], 0, v[128:129]
	s_add_i32 m0, s5, 0x1e000
	v_and_b32_e32 v7, 15, v1
	global_load_lds_dwordx4 v[8:9], off
	v_bfe_u32 v8, v1, 4, 2
	v_lshlrev_b32_e32 v9, 4, v8
	v_lshlrev_b32_e32 v1, 2, v1
	v_lshl_or_b32 v192, s10, 6, v7
	v_lshl_or_b32 v7, v7, 6, v9
	v_and_b32_e32 v1, 32, v1
	v_bitop3_b32 v9, v7, s11, v1 bitop3:0xde
	v_bitop3_b32 v193, v7, s12, v1 bitop3:0xde
	v_lshlrev_b32_e32 v1, 10, v4
	v_and_b32_e32 v1, 0xfffff800, v1
	v_lshl_add_u32 v1, v5, 7, v1
	v_and_b32_e32 v4, 1, v4
	v_lshl_or_b32 v1, v4, 6, v1
	v_lshl_add_u32 v130, v6, 1, v1
	v_lshlrev_b32_e32 v1, 10, v0
	v_and_b32_e32 v1, 0xfffff800, v1
	s_waitcnt vmcnt(0)
	v_lshl_add_u32 v1, v2, 7, v1
	v_and_b32_e32 v0, 1, v0
	s_cmpk_lt_u32 s0, 0x100
	v_lshl_or_b32 v194, v8, 2, s1
	v_lshl_or_b32 v0, v0, 6, v1
	v_readlane_b32 s0, v249, 33
	v_readlane_b32 s38, v249, 29
	s_cselect_b64 s[46:47], -1, 0
	s_mov_b32 s76, 0
	v_cmp_eq_u32_e64 s[40:41], 0, v8
	v_mov_b32_e32 v131, v177
	v_lshl_add_u32 v132, v3, 1, v0
	v_mov_b32_e32 v133, v177
	v_add_u32_e32 v195, 0, v9
	v_readlane_b32 s10, v250, 31
	v_readlane_b32 s64, v249, 19
	v_readlane_b32 s1, v249, 34
	v_readlane_b32 s39, v249, 30
	s_barrier
	v_readlane_b32 s65, v249, 20
	s_branch .LBB0_872

; #define PG8_STAGE(bufoff, gbase, voff) do { _Pragma("unroll") for (int _i = 0; _i < 2; ++_i) \
;         __builtin_amdgcn_global_load_lds((const unsigned*)((const char*)(gbase) + (voff)[_i]), (PG8_LAS unsigned*)(lds + (bufoff) + ldsw + _i * 8192), 16, 0, 0); } while (0)
; #define PG8_LDA(dst, b, h) do { _Pragma("unroll") for (int m = 0; m < 4; ++m) _Pragma("unroll") for (int k = 0; k < 2; ++k) dst[m][k] = *(const PG8_LAS bf16x8*)(lds + PG8_SA(b, h) + aoff + m * 2048 + k * 1024); } while (0)
; #define PG8_LDB(dst, b, h) do { _Pragma("unroll") for (int n = 0; n < 2; ++n) _Pragma("unroll") for (int k = 0; k < 2; ++k) dst[n][k] = *(const PG8_LAS bf16x8*)(lds + PG8_SB(b, h) + boff + n * 2048 + k * 1024); } while (0)
; #define PG8_MMA(ai, bj, At, Bt) do { __builtin_amdgcn_s_setprio(1); _Pragma("unroll") for (int m = 0; m < 4; ++m) _Pragma("unroll") for (int n = 0; n < 2; ++n) _Pragma("unroll") for (int k = 0; k < 2; ++k) \
;         acc[ai][bj][m][n] = __builtin_amdgcn_mfma_f32_16x16x32_bf16(Bt[n][k], At[m][k], acc[ai][bj][m][n], 0, 0, 0); __builtin_amdgcn_s_setprio(0); } while (0)
; #define PG8_WAIT_V(n) asm volatile("s_waitcnt vmcnt(" #n ")" ::: "memory")
; #define PG8_WAIT_L(n) asm volatile("s_waitcnt lgkmcnt(" #n ")" ::: "memory")
; #define PG8_BAR __builtin_amdgcn_s_barrier()
; #define PG8_SCHED __builtin_amdgcn_sched_barrier(0)
; template <class Epi, class Sched, bool ALIGN_EPI = false, bool SP2 = false, bool TILED = false>
; __device__ __forceinline__ void gemm_phase(PG8_LAS unsigned char* lds, const Gemm g, const Sched& S, const Epi& E) {
;     ...
;             PG8_LDB(B0, 0, 0); PG8_LDB(B1, 0, 1); PG8_SCHED; PG8_LDA(At, 0, 0); PG8_STAGE(PG8_SA(1, 1), a1 + hstep, voffA);
;             PG8_WAIT_V(8); PG8_WAIT_L(0); PG8_BAR; PG8_MMA(0, 0, At, B0); PG8_MMA(0, 1, At, B1); PG8_BAR; PG8_SCHED;
;             PG8_LDA(At, 0, 1); PG8_STAGE(PG8_SB(0, 0), b2, voffB); PG8_STAGE(PG8_SB(0, 1), b2 + hstep, voffB); PG8_STAGE(PG8_SA(0, 0), a2, voffA);
.LBB0_879:
	s_add_u32 s0, s66, 0x4000
	s_addc_u32 s1, s67, 0
	s_cmp_eq_u32 s79, 60
	s_cselect_b32 s72, s51, s0
	s_cselect_b32 s73, s11, s1
	s_cselect_b32 s38, s65, s77
	s_cselect_b32 s39, s49, s78
	s_add_u32 s0, s72, 0x8000
	s_addc_u32 s1, s73, 0
	s_add_i32 s12, 0, 0x10000
	s_add_i32 s35, 0, 0x14000
	v_add_u32_e32 v146, s12, v193
	v_add_u32_e32 v162, s35, v193
	ds_read_b128 v[134:137], v146
	ds_read_b128 v[138:141], v146 offset:1024
	ds_read_b128 v[142:145], v146 offset:2048
	ds_read_b128 v[146:149], v146 offset:3072
	ds_read_b128 v[150:153], v162
	ds_read_b128 v[154:157], v162 offset:1024
	ds_read_b128 v[158:161], v162 offset:2048
	ds_read_b128 v[162:165], v162 offset:3072
	v_lshl_add_u64 v[174:175], s[66:67], 0, v[130:131]
	s_add_i32 m0, s5, 0xc000
	ds_read_b128 v[166:169], v195
	ds_read_b128 v[170:173], v195 offset:1024
	ds_read_b128 v[196:199], v195 offset:2048
	ds_read_b128 v[200:203], v195 offset:3072
	ds_read_b128 v[204:207], v195 offset:4096
	ds_read_b128 v[220:223], v195 offset:5120
	ds_read_b128 v[224:227], v195 offset:6144
	ds_read_b128 v[228:231], v195 offset:7168
	global_load_lds_dwordx4 v[174:175], off
	v_lshl_add_u64 v[174:175], s[66:67], 0, v[132:133]
	s_add_i32 m0, s5, 0xe000
	s_nop 0
	global_load_lds_dwordx4 v[174:175], off
	s_cmp_eq_u32 s79, -2
	s_cbranch_scc1 .Lmyw_8
	s_waitcnt vmcnt(8)
.Lmyw_8:
	s_waitcnt lgkmcnt(0)
	s_barrier
	s_setprio 1
	s_waitcnt lgkmcnt(0)
	v_mfma_f32_16x16x32_bf16 v[124:127], v[134:137], v[166:169], v[124:127]
	v_mfma_f32_16x16x32_bf16 v[120:123], v[142:145], v[166:169], v[120:123]
	v_mfma_f32_16x16x32_bf16 v[108:111], v[134:137], v[196:199], v[108:111]
	v_mfma_f32_16x16x32_bf16 v[104:107], v[142:145], v[196:199], v[104:107]
	v_mfma_f32_16x16x32_bf16 v[92:95], v[134:137], v[204:207], v[92:95]
	v_mfma_f32_16x16x32_bf16 v[88:91], v[142:145], v[204:207], v[88:91]
	v_mfma_f32_16x16x32_bf16 v[76:79], v[134:137], v[224:227], v[76:79]
	v_mfma_f32_16x16x32_bf16 v[72:75], v[142:145], v[224:227], v[72:75]
	v_mfma_f32_16x16x32_bf16 v[124:127], v[138:141], v[170:173], v[124:127]
	v_mfma_f32_16x16x32_bf16 v[120:123], v[146:149], v[170:173], v[120:123]
	v_mfma_f32_16x16x32_bf16 v[108:111], v[138:141], v[200:203], v[108:111]
	v_mfma_f32_16x16x32_bf16 v[104:107], v[146:149], v[200:203], v[104:107]
	v_mfma_f32_16x16x32_bf16 v[92:95], v[138:141], v[220:223], v[92:95]
	v_mfma_f32_16x16x32_bf16 v[88:91], v[146:149], v[220:223], v[88:91]
	v_mfma_f32_16x16x32_bf16 v[76:79], v[138:141], v[228:231], v[76:79]
	v_mfma_f32_16x16x32_bf16 v[72:75], v[146:149], v[228:231], v[72:75]
	s_setprio 0
	s_setprio 1
	v_mfma_f32_16x16x32_bf16 v[116:119], v[150:153], v[166:169], v[116:119]
	v_mfma_f32_16x16x32_bf16 v[112:115], v[158:161], v[166:169], v[112:115]
	v_mfma_f32_16x16x32_bf16 v[100:103], v[150:153], v[196:199], v[100:103]
	v_mfma_f32_16x16x32_bf16 v[96:99], v[158:161], v[196:199], v[96:99]
	v_mfma_f32_16x16x32_bf16 v[84:87], v[150:153], v[204:207], v[84:87]
	v_mfma_f32_16x16x32_bf16 v[80:83], v[158:161], v[204:207], v[80:83]
	v_mfma_f32_16x16x32_bf16 v[68:71], v[150:153], v[224:227], v[68:71]
	v_mfma_f32_16x16x32_bf16 v[64:67], v[158:161], v[224:227], v[64:67]
	v_mfma_f32_16x16x32_bf16 v[116:119], v[154:157], v[170:173], v[116:119]
	v_mfma_f32_16x16x32_bf16 v[112:115], v[162:165], v[170:173], v[112:115]
	v_mfma_f32_16x16x32_bf16 v[100:103], v[154:157], v[200:203], v[100:103]
	v_mfma_f32_16x16x32_bf16 v[96:99], v[162:165], v[200:203], v[96:99]
	v_mfma_f32_16x16x32_bf16 v[84:87], v[154:157], v[220:223], v[84:87]
	v_mfma_f32_16x16x32_bf16 v[80:83], v[162:165], v[220:223], v[80:83]
	v_mfma_f32_16x16x32_bf16 v[68:71], v[154:157], v[228:231], v[68:71]
	v_mfma_f32_16x16x32_bf16 v[64:67], v[162:165], v[228:231], v[64:67]
	s_setprio 0
	s_barrier
	s_add_i32 s12, s12, s4
	v_lshl_add_u64 v[174:175], s[38:39], 0, v[176:177]
	s_mov_b32 m0, s12
	ds_read_b128 v[166:169], v195 offset:16384
	ds_read_b128 v[170:173], v195 offset:17408
	ds_read_b128 v[196:199], v195 offset:18432
	ds_read_b128 v[200:203], v195 offset:19456
	ds_read_b128 v[204:207], v195 offset:20480
	ds_read_b128 v[220:223], v195 offset:21504
	ds_read_b128 v[224:227], v195 offset:22528
	ds_read_b128 v[228:231], v195 offset:23552
	global_load_lds_dwordx4 v[174:175], off
	s_add_i32 m0, s12, 0x2000
	s_add_u32 s20, s38, 0x4000
	v_lshl_add_u64 v[174:175], s[38:39], 0, v[128:129]
	s_addc_u32 s21, s39, 0
	s_add_i32 s12, s35, s4
	global_load_lds_dwordx4 v[174:175], off
	v_lshl_add_u64 v[174:175], s[20:21], 0, v[176:177]
	s_mov_b32 m0, s12
	s_nop 0
	global_load_lds_dwordx4 v[174:175], off
	v_lshl_add_u64 v[174:175], s[20:21], 0, v[128:129]
	s_add_i32 m0, s12, 0x2000
	s_nop 0
	global_load_lds_dwordx4 v[174:175], off
	v_lshl_add_u64 v[174:175], s[72:73], 0, v[176:177]
	s_mov_b32 m0, s5
	s_nop 0
	global_load_lds_dwordx4 v[174:175], off
	v_lshl_add_u64 v[174:175], s[72:73], 0, v[128:129]
	s_mov_b32 m0, s6
	s_nop 0
	global_load_lds_dwordx4 v[174:175], off
	s_cmp_eq_u32 s79, -2
	s_cbranch_scc1 .Lmyw_9
	s_waitcnt vmcnt(8)
; #define PG8_STAGE(bufoff, gbase, voff) do { _Pragma("unroll") for (int _i = 0; _i < 2; ++_i) \
;         __builtin_amdgcn_global_load_lds((const unsigned*)((const char*)(gbase) + (voff)[_i]), (PG8_LAS unsigned*)(lds + (bufoff) + ldsw + _i * 8192), 16, 0, 0); } while (0)
; #define PG8_LDA(dst, b, h) do { _Pragma("unroll") for (int m = 0; m < 4; ++m) _Pragma("unroll") for (int k = 0; k < 2; ++k) dst[m][k] = *(const PG8_LAS bf16x8*)(lds + PG8_SA(b, h) + aoff + m * 2048 + k * 1024); } while (0)
; #define PG8_LDB(dst, b, h) do { _Pragma("unroll") for (int n = 0; n < 2; ++n) _Pragma("unroll") for (int k = 0; k < 2; ++k) dst[n][k] = *(const PG8_LAS bf16x8*)(lds + PG8_SB(b, h) + boff + n * 2048 + k * 1024); } while (0)
; #define PG8_MMA(ai, bj, At, Bt) do { __builtin_amdgcn_s_setprio(1); _Pragma("unroll") for (int m = 0; m < 4; ++m) _Pragma("unroll") for (int n = 0; n < 2; ++n) _Pragma("unroll") for (int k = 0; k < 2; ++k) \
;         acc[ai][bj][m][n] = __builtin_amdgcn_mfma_f32_16x16x32_bf16(Bt[n][k], At[m][k], acc[ai][bj][m][n], 0, 0, 0); __builtin_amdgcn_s_setprio(0); } while (0)
; #define PG8_WAIT_V(n) asm volatile("s_waitcnt vmcnt(" #n ")" ::: "memory")
; #define PG8_WAIT_L(n) asm volatile("s_waitcnt lgkmcnt(" #n ")" ::: "memory")
; #define PG8_BAR __builtin_amdgcn_s_barrier()
; #define PG8_SCHED __builtin_amdgcn_sched_barrier(0)
; template <class Epi, class Sched, bool ALIGN_EPI = false, bool SP2 = false, bool TILED = false>
; __device__ __forceinline__ void gemm_phase(PG8_LAS unsigned char* lds, const Gemm g, const Sched& S, const Epi& E) {
;     ...
;             PG8_WAIT_V(8); PG8_WAIT_L(0); PG8_BAR; PG8_MMA(1, 0, At, B0); PG8_MMA(1, 1, At, B1); PG8_BAR; PG8_SCHED;
;             PG8_LDB(B0, 1, 0); PG8_LDB(B1, 1, 1); PG8_SCHED; PG8_LDA(At, 1, 0); PG8_STAGE(PG8_SA(0, 1), a2 + hstep, voffA);
;             PG8_WAIT_V(8); PG8_WAIT_L(0); PG8_BAR; PG8_MMA(0, 0, At, B0); PG8_MMA(0, 1, At, B1); PG8_BAR; PG8_SCHED;
.Lmyw_9:
	s_waitcnt lgkmcnt(0)
	s_barrier
	s_setprio 1
	s_waitcnt lgkmcnt(0)
	v_mfma_f32_16x16x32_bf16 v[60:63], v[134:137], v[166:169], v[60:63]
	v_mfma_f32_16x16x32_bf16 v[56:59], v[142:145], v[166:169], v[56:59]
	v_mfma_f32_16x16x32_bf16 v[44:47], v[134:137], v[196:199], v[44:47]
	v_mfma_f32_16x16x32_bf16 v[40:43], v[142:145], v[196:199], v[40:43]
	v_mfma_f32_16x16x32_bf16 v[28:31], v[134:137], v[204:207], v[28:31]
	v_mfma_f32_16x16x32_bf16 v[24:27], v[142:145], v[204:207], v[24:27]
	v_mfma_f32_16x16x32_bf16 v[12:15], v[134:137], v[224:227], v[12:15]
	v_mfma_f32_16x16x32_bf16 v[8:11], v[142:145], v[224:227], v[8:11]
	v_mfma_f32_16x16x32_bf16 v[60:63], v[138:141], v[170:173], v[60:63]
	v_mfma_f32_16x16x32_bf16 v[56:59], v[146:149], v[170:173], v[56:59]
	v_mfma_f32_16x16x32_bf16 v[44:47], v[138:141], v[200:203], v[44:47]
	v_mfma_f32_16x16x32_bf16 v[40:43], v[146:149], v[200:203], v[40:43]
	v_mfma_f32_16x16x32_bf16 v[28:31], v[138:141], v[220:223], v[28:31]
	v_mfma_f32_16x16x32_bf16 v[24:27], v[146:149], v[220:223], v[24:27]
	v_mfma_f32_16x16x32_bf16 v[12:15], v[138:141], v[228:231], v[12:15]
	v_mfma_f32_16x16x32_bf16 v[8:11], v[146:149], v[228:231], v[8:11]
	s_setprio 0
	s_setprio 1
	v_mfma_f32_16x16x32_bf16 v[52:55], v[150:153], v[166:169], v[52:55]
	v_mfma_f32_16x16x32_bf16 v[48:51], v[158:161], v[166:169], v[48:51]
	v_mfma_f32_16x16x32_bf16 v[36:39], v[150:153], v[196:199], v[36:39]
	v_mfma_f32_16x16x32_bf16 v[32:35], v[158:161], v[196:199], v[32:35]
	v_mfma_f32_16x16x32_bf16 v[20:23], v[150:153], v[204:207], v[20:23]
	v_mfma_f32_16x16x32_bf16 v[16:19], v[158:161], v[204:207], v[16:19]
	v_mfma_f32_16x16x32_bf16 v[4:7], v[150:153], v[224:227], v[4:7]
	v_mfma_f32_16x16x32_bf16 v[0:3], v[158:161], v[224:227], v[0:3]
	v_mfma_f32_16x16x32_bf16 v[52:55], v[154:157], v[170:173], v[52:55]
	v_mfma_f32_16x16x32_bf16 v[48:51], v[162:165], v[170:173], v[48:51]
	v_mfma_f32_16x16x32_bf16 v[36:39], v[154:157], v[200:203], v[36:39]
	v_mfma_f32_16x16x32_bf16 v[32:35], v[162:165], v[200:203], v[32:35]
	v_mfma_f32_16x16x32_bf16 v[20:23], v[154:157], v[220:223], v[20:23]
	v_mfma_f32_16x16x32_bf16 v[16:19], v[162:165], v[220:223], v[16:19]
	v_mfma_f32_16x16x32_bf16 v[4:7], v[154:157], v[228:231], v[4:7]
	v_mfma_f32_16x16x32_bf16 v[0:3], v[162:165], v[228:231], v[0:3]
	s_setprio 0
	s_barrier
	s_add_i32 s12, 0, 0x18000
	s_add_i32 s35, 0, 0x1c000
	v_add_u32_e32 v146, s12, v193
	v_add_u32_e32 v162, s35, v193
	ds_read_b128 v[134:137], v146
	ds_read_b128 v[138:141], v146 offset:1024
	ds_read_b128 v[142:145], v146 offset:2048
	ds_read_b128 v[146:149], v146 offset:3072
	ds_read_b128 v[150:153], v162
	ds_read_b128 v[154:157], v162 offset:1024
	ds_read_b128 v[158:161], v162 offset:2048
	ds_read_b128 v[162:165], v162 offset:3072
	s_add_u32 s20, s72, 0x4000
	s_addc_u32 s21, s73, 0
	s_mov_b32 m0, s7
	v_lshl_add_u64 v[174:175], s[20:21], 0, v[176:177]
	ds_read_b128 v[166:169], v195 offset:32768
	ds_read_b128 v[170:173], v195 offset:33792
	ds_read_b128 v[196:199], v195 offset:34816
	ds_read_b128 v[200:203], v195 offset:35840
	ds_read_b128 v[204:207], v195 offset:36864
	ds_read_b128 v[220:223], v195 offset:37888
	ds_read_b128 v[224:227], v195 offset:38912
	ds_read_b128 v[228:231], v195 offset:39936
	global_load_lds_dwordx4 v[174:175], off
	v_lshl_add_u64 v[174:175], s[20:21], 0, v[128:129]
	s_mov_b32 m0, s8
	s_nop 0
	global_load_lds_dwordx4 v[174:175], off
	s_waitcnt vmcnt(8)
	s_waitcnt lgkmcnt(0)
	s_barrier
	s_setprio 1
	s_waitcnt lgkmcnt(0)
	v_mfma_f32_16x16x32_bf16 v[124:127], v[134:137], v[166:169], v[124:127]
	v_mfma_f32_16x16x32_bf16 v[120:123], v[142:145], v[166:169], v[120:123]
	v_mfma_f32_16x16x32_bf16 v[108:111], v[134:137], v[196:199], v[108:111]
	v_mfma_f32_16x16x32_bf16 v[104:107], v[142:145], v[196:199], v[104:107]
	v_mfma_f32_16x16x32_bf16 v[92:95], v[134:137], v[204:207], v[92:95]
	v_mfma_f32_16x16x32_bf16 v[88:91], v[142:145], v[204:207], v[88:91]
	v_mfma_f32_16x16x32_bf16 v[76:79], v[134:137], v[224:227], v[76:79]
	v_mfma_f32_16x16x32_bf16 v[72:75], v[142:145], v[224:227], v[72:75]
	v_mfma_f32_16x16x32_bf16 v[124:127], v[138:141], v[170:173], v[124:127]
	v_mfma_f32_16x16x32_bf16 v[120:123], v[146:149], v[170:173], v[120:123]
	v_mfma_f32_16x16x32_bf16 v[108:111], v[138:141], v[200:203], v[108:111]
	v_mfma_f32_16x16x32_bf16 v[104:107], v[146:149], v[200:203], v[104:107]
	v_mfma_f32_16x16x32_bf16 v[92:95], v[138:141], v[220:223], v[92:95]
	v_mfma_f32_16x16x32_bf16 v[88:91], v[146:149], v[220:223], v[88:91]
	v_mfma_f32_16x16x32_bf16 v[76:79], v[138:141], v[228:231], v[76:79]
	v_mfma_f32_16x16x32_bf16 v[72:75], v[146:149], v[228:231], v[72:75]
	s_setprio 0
	s_setprio 1
	v_mfma_f32_16x16x32_bf16 v[116:119], v[150:153], v[166:169], v[116:119]
	v_mfma_f32_16x16x32_bf16 v[112:115], v[158:161], v[166:169], v[112:115]
	v_mfma_f32_16x16x32_bf16 v[100:103], v[150:153], v[196:199], v[100:103]
	v_mfma_f32_16x16x32_bf16 v[96:99], v[158:161], v[196:199], v[96:99]
	v_mfma_f32_16x16x32_bf16 v[84:87], v[150:153], v[204:207], v[84:87]
	v_mfma_f32_16x16x32_bf16 v[80:83], v[158:161], v[204:207], v[80:83]
	v_mfma_f32_16x16x32_bf16 v[68:71], v[150:153], v[224:227], v[68:71]
	v_mfma_f32_16x16x32_bf16 v[64:67], v[158:161], v[224:227], v[64:67]
	v_mfma_f32_16x16x32_bf16 v[116:119], v[154:157], v[170:173], v[116:119]
	v_mfma_f32_16x16x32_bf16 v[112:115], v[162:165], v[170:173], v[112:115]
	v_mfma_f32_16x16x32_bf16 v[100:103], v[154:157], v[200:203], v[100:103]
	v_mfma_f32_16x16x32_bf16 v[96:99], v[162:165], v[200:203], v[96:99]
	v_mfma_f32_16x16x32_bf16 v[84:87], v[154:157], v[220:223], v[84:87]
	v_mfma_f32_16x16x32_bf16 v[80:83], v[162:165], v[220:223], v[80:83]
	v_mfma_f32_16x16x32_bf16 v[68:71], v[154:157], v[228:231], v[68:71]
	v_mfma_f32_16x16x32_bf16 v[64:67], v[162:165], v[228:231], v[64:67]
	s_setprio 0
	s_barrier
; #define PG8_STAGE(bufoff, gbase, voff) do { _Pragma("unroll") for (int _i = 0; _i < 2; ++_i) \
;         __builtin_amdgcn_global_load_lds((const unsigned*)((const char*)(gbase) + (voff)[_i]), (PG8_LAS unsigned*)(lds + (bufoff) + ldsw + _i * 8192), 16, 0, 0); } while (0)
; #define PG8_LDA(dst, b, h) do { _Pragma("unroll") for (int m = 0; m < 4; ++m) _Pragma("unroll") for (int k = 0; k < 2; ++k) dst[m][k] = *(const PG8_LAS bf16x8*)(lds + PG8_SA(b, h) + aoff + m * 2048 + k * 1024); } while (0)
; #define PG8_MMA(ai, bj, At, Bt) do { __builtin_amdgcn_s_setprio(1); _Pragma("unroll") for (int m = 0; m < 4; ++m) _Pragma("unroll") for (int n = 0; n < 2; ++n) _Pragma("unroll") for (int k = 0; k < 2; ++k) \
;         acc[ai][bj][m][n] = __builtin_amdgcn_mfma_f32_16x16x32_bf16(Bt[n][k], At[m][k], acc[ai][bj][m][n], 0, 0, 0); __builtin_amdgcn_s_setprio(0); } while (0)
; #define PG8_WAIT_V(n) asm volatile("s_waitcnt vmcnt(" #n ")" ::: "memory")
; #define PG8_WAIT_L(n) asm volatile("s_waitcnt lgkmcnt(" #n ")" ::: "memory")
; #define PG8_BAR __builtin_amdgcn_s_barrier()
; #define PG8_SCHED __builtin_amdgcn_sched_barrier(0)
; template <class Epi, class Sched, bool ALIGN_EPI = false, bool SP2 = false, bool TILED = false>
; __device__ __forceinline__ void gemm_phase(PG8_LAS unsigned char* lds, const Gemm g, const Sched& S, const Epi& E) {
;     ...
;             PG8_LDA(At, 1, 1); PG8_STAGE(PG8_SB(1, 0), b3, voffB); PG8_STAGE(PG8_SB(1, 1), b3 + hstep, voffB); PG8_STAGE(PG8_SA(1, 0), a3, voffA);
;             PG8_WAIT_V(8); PG8_WAIT_L(0); PG8_BAR; PG8_MMA(1, 0, At, B0); PG8_MMA(1, 1, At, B1); PG8_BAR; PG8_SCHED;
	s_add_u32 s20, s38, 0x8000
	s_addc_u32 s21, s39, 0
	s_add_i32 s12, s12, s4
	v_lshl_add_u64 v[174:175], s[20:21], 0, v[176:177]
	s_mov_b32 m0, s12
	ds_read_b128 v[166:169], v195 offset:49152
	ds_read_b128 v[170:173], v195 offset:50176
	ds_read_b128 v[196:199], v195 offset:51200
	ds_read_b128 v[200:203], v195 offset:52224
	ds_read_b128 v[204:207], v195 offset:53248
	ds_read_b128 v[220:223], v195 offset:54272
	ds_read_b128 v[224:227], v195 offset:55296
	ds_read_b128 v[228:231], v195 offset:56320
	global_load_lds_dwordx4 v[174:175], off
	s_add_i32 m0, s12, 0x2000
	v_lshl_add_u64 v[174:175], s[20:21], 0, v[128:129]
	s_add_u32 s20, s38, 0xc000
	s_addc_u32 s21, s39, 0
	s_add_i32 s12, s35, s4
	global_load_lds_dwordx4 v[174:175], off
	v_lshl_add_u64 v[174:175], s[20:21], 0, v[176:177]
	s_mov_b32 m0, s12
	s_nop 0
	global_load_lds_dwordx4 v[174:175], off
	v_lshl_add_u64 v[174:175], s[20:21], 0, v[128:129]
	s_add_i32 m0, s12, 0x2000
	s_nop 0
	global_load_lds_dwordx4 v[174:175], off
	v_lshl_add_u64 v[174:175], s[0:1], 0, v[176:177]
	s_mov_b32 m0, s54
	s_nop 0
	global_load_lds_dwordx4 v[174:175], off
	v_lshl_add_u64 v[174:175], s[0:1], 0, v[128:129]
	s_mov_b32 m0, s55
	s_nop 0
	global_load_lds_dwordx4 v[174:175], off
	s_waitcnt vmcnt(8)
	s_waitcnt lgkmcnt(0)
	s_barrier
	s_setprio 1
	s_waitcnt lgkmcnt(0)
	v_mfma_f32_16x16x32_bf16 v[60:63], v[134:137], v[166:169], v[60:63]
	v_mfma_f32_16x16x32_bf16 v[56:59], v[142:145], v[166:169], v[56:59]
	v_mfma_f32_16x16x32_bf16 v[44:47], v[134:137], v[196:199], v[44:47]
	v_mfma_f32_16x16x32_bf16 v[40:43], v[142:145], v[196:199], v[40:43]
	v_mfma_f32_16x16x32_bf16 v[28:31], v[134:137], v[204:207], v[28:31]
	v_mfma_f32_16x16x32_bf16 v[24:27], v[142:145], v[204:207], v[24:27]
	v_mfma_f32_16x16x32_bf16 v[12:15], v[134:137], v[224:227], v[12:15]
	v_mfma_f32_16x16x32_bf16 v[8:11], v[142:145], v[224:227], v[8:11]
	v_mfma_f32_16x16x32_bf16 v[60:63], v[138:141], v[170:173], v[60:63]
	v_mfma_f32_16x16x32_bf16 v[56:59], v[146:149], v[170:173], v[56:59]
	v_mfma_f32_16x16x32_bf16 v[44:47], v[138:141], v[200:203], v[44:47]
	v_mfma_f32_16x16x32_bf16 v[40:43], v[146:149], v[200:203], v[40:43]
	v_mfma_f32_16x16x32_bf16 v[28:31], v[138:141], v[220:223], v[28:31]
	v_mfma_f32_16x16x32_bf16 v[24:27], v[146:149], v[220:223], v[24:27]
	v_mfma_f32_16x16x32_bf16 v[12:15], v[138:141], v[228:231], v[12:15]
	v_mfma_f32_16x16x32_bf16 v[8:11], v[146:149], v[228:231], v[8:11]
	s_setprio 0
	s_setprio 1
	v_mfma_f32_16x16x32_bf16 v[52:55], v[150:153], v[166:169], v[52:55]
	v_mfma_f32_16x16x32_bf16 v[48:51], v[158:161], v[166:169], v[48:51]
	v_mfma_f32_16x16x32_bf16 v[36:39], v[150:153], v[196:199], v[36:39]
	v_mfma_f32_16x16x32_bf16 v[32:35], v[158:161], v[196:199], v[32:35]
	v_mfma_f32_16x16x32_bf16 v[20:23], v[150:153], v[204:207], v[20:23]
	v_mfma_f32_16x16x32_bf16 v[16:19], v[158:161], v[204:207], v[16:19]
	v_mfma_f32_16x16x32_bf16 v[4:7], v[150:153], v[224:227], v[4:7]
	v_mfma_f32_16x16x32_bf16 v[0:3], v[158:161], v[224:227], v[0:3]
	v_mfma_f32_16x16x32_bf16 v[52:55], v[154:157], v[170:173], v[52:55]
	v_mfma_f32_16x16x32_bf16 v[48:51], v[162:165], v[170:173], v[48:51]
	v_mfma_f32_16x16x32_bf16 v[36:39], v[154:157], v[200:203], v[36:39]
	v_mfma_f32_16x16x32_bf16 v[32:35], v[162:165], v[200:203], v[32:35]
	v_mfma_f32_16x16x32_bf16 v[20:23], v[154:157], v[220:223], v[20:23]
	v_mfma_f32_16x16x32_bf16 v[16:19], v[162:165], v[220:223], v[16:19]
	v_mfma_f32_16x16x32_bf16 v[4:7], v[154:157], v[228:231], v[4:7]
	v_mfma_f32_16x16x32_bf16 v[0:3], v[162:165], v[228:231], v[0:3]
	s_setprio 0
	s_barrier
	s_add_i32 s79, s79, 2
	s_add_u32 s66, s66, 0x10000
	s_addc_u32 s67, s67, 0
	s_add_u32 s77, s77, 0x10000
	s_addc_u32 s78, s78, 0
	s_cmp_gt_u32 s79, 61
	s_cbranch_scc0 .LBB0_879
	s_and_b64 vcc, exec, s[46:47]
	s_cbranch_vccz .LBB0_882
	s_barrier
